# finalize_tile transposed V write: 32 serialized LDS read round trips per thread batched into 8 (8 u16 reads per 16-byte store, one wait)
# baseline (speedup 1.0000x reference)
; DI void finalize_tile(const Params& p, int l, int tile, LAS unsigned char* lds, int tid, int lane, int wave, const bool doq = true) {
;     ...
;     const int sub = lane >> 4, i = lane & 15;
;     const int t0 = tile * 64;
;     const float* qg = (const float*)(p.ws + WS_SM) + 1536 + l * 192; const float* kg = (const float*)(p.ws + WS_SM) + 2304 + l * 192;
; #pragma unroll
;     for (int it = 0; it < 2; ++it) {
;         const int tl = wave * 8 + it * 4 + sub; const size_t t = (size_t)(t0 + tl);
;         const u32x4 c0 = *(const u32x4*)(CQ + t * 256 + 16 * i), c1 = *(const u32x4*)(CQ + t * 256 + 16 * i + 8);
;         const u32x4 kvw = *(const u32x4*)(MISC + t * 256 + 8 * i);
;         const unsigned p1 = *(const unsigned*)(MISC + t * 256 + 128 + 2 * i), p2 = *(const unsigned*)(MISC + t * 256 + 160 + 2 * i);
;         const f32x2 cs = *(const f32x2*)(COS + t * 32 + 2 * i), sn = *(const f32x2*)(SIN + t * 32 + 2 * i);
;         float v[8], w[8]; float s1 = 0.f, s2 = 0.f;
;         unpack8(c0, v); unpack8(c1, w);
; #pragma unroll
;         for (int e = 0; e < 8; ++e) s1 += v[e] * v[e] + w[e] * w[e];
;         unpack8(kvw, v);
; #pragma unroll
;         for (int e = 0; e < 8; ++e) s2 += v[e] * v[e];
;         const float x1a = bflo(p1), x1b = bfhi(p1), x2a = bflo(p2), x2b = bfhi(p2);
;         float s3 = (x1a * x1a + x1b * x1b) + (x2a * x2a + x2b * x2b);
;         s1 = red16(s1, lane); s2 = red16(s2, lane); s3 = red16(s3, lane);
;         const float rcq = rsqrtf(s1 * (1.0f / 256.0f) + EPS), rckv = rsqrtf(s2 * (1.0f / 128.0f) + EPS);
;         u32x4 qa4[4], ka4[4], va4[4]; unsigned r14[4], r24[4];
; #pragma unroll
;         for (int h = 0; h < 4; ++h) { const bf16_t* qp = QR + t * 768 + h * 192; const bf16_t* kp = KVR + t * 1024 + h * 256;
;             qa4[h] = *(const u32x4*)(qp + 8 * i); r14[h] = *(const unsigned*)(qp + 128 + 2 * i); r24[h] = *(const unsigned*)(qp + 160 + 2 * i);
;             ka4[h] = *(const u32x4*)(kp + 8 * i); va4[h] = *(const u32x4*)(kp + 128 + 8 * i); }
;         const f32x4 qg0 = *(const f32x4*)(qg + 8 * i), qg1 = *(const f32x4*)(qg + 8 * i + 4), kg0 = *(const f32x4*)(kg + 8 * i), kg1 = *(const f32x4*)(kg + 8 * i + 4);
;         const f32x2 qgr1 = *(const f32x2*)(qg + 128 + 2 * i), qgr2 = *(const f32x2*)(qg + 160 + 2 * i), kgr1 = *(const f32x2*)(kg + 128 + 2 * i), kgr2 = *(const f32x2*)(kg + 160 + 2 * i);
.LBB0_366:
	s_mov_b32 s2, s33
	s_mov_b64 s[6:7], s[50:51]
	v_mbcnt_lo_u32_b32 v0, -1, 0
	v_mbcnt_hi_u32_b32 v0, -1, v0
	s_add_u32 s10, s6, 0x8e00000
	s_addc_u32 s11, s7, 0
	s_add_u32 s14, s6, 0x9600000
	s_addc_u32 s15, s7, 0
	s_add_u32 s8, s6, 0xae00000
	s_addc_u32 s9, s7, 0
	s_add_u32 s12, s6, 0xce00000
	s_addc_u32 s13, s7, 0
	s_add_u32 s3, s6, s4
	s_addc_u32 s17, s7, s5
	v_ashrrev_i32_e32 v2, 4, v0
	v_and_b32_e32 v16, 15, v0
	s_add_u32 s0, s3, 0x31800
	s_addc_u32 s1, s17, 0
	v_lshl_add_u32 v93, s2, 3, v2
	v_lshlrev_b32_e32 v2, 5, v16
	v_mov_b32_e32 v3, v1
	v_lshl_add_u32 v92, s2, 6, v0
	s_add_u32 s16, s3, 0x32400
	v_lshl_add_u64 v[4:5], s[6:7], 0, v[2:3]
	s_mov_b64 s[2:3], 0x8600000
	v_lshl_add_u64 v[52:53], v[4:5], 0, s[2:3]
	v_lshlrev_b32_e32 v4, 3, v16
	v_mov_b32_e32 v5, v1
	v_add_u32_e32 v58, s19, v93
	v_lshl_add_u64 v[6:7], s[6:7], 0, v[4:5]
	s_mov_b64 s[2:3], 0x2100000
	v_ashrrev_i32_e32 v59, 31, v58
	v_lshl_add_u64 v[54:55], v[6:7], 0, s[2:3]
	s_mov_b64 s[2:3], 0x2300000
	v_lshlrev_b64 v[10:11], 9, v[58:59]
	s_addc_u32 s17, s17, 0
	v_lshl_add_u64 v[56:57], v[6:7], 0, s[2:3]
	v_lshl_add_u64 v[6:7], v[52:53], 0, v[10:11]
	v_lshl_add_u64 v[66:67], s[0:1], 0, v[2:3]
	v_lshl_add_u64 v[64:65], s[16:17], 0, v[2:3]
	v_lshl_add_u64 v[62:63], s[0:1], 0, v[4:5]
	v_lshl_add_u64 v[60:61], s[16:17], 0, v[4:5]
	flat_load_dwordx4 v[2:5], v[6:7]
	s_nop 0
	flat_load_dwordx4 v[6:9], v[6:7] offset:16
	v_lshlrev_b32_e32 v0, 4, v16
	v_lshl_add_u64 v[14:15], s[10:11], 0, v[10:11]
	v_lshl_add_u64 v[10:11], v[14:15], 0, v[0:1]
	flat_load_dwordx4 v[10:13], v[10:11]
	v_lshlrev_b32_e32 v50, 2, v16
	v_mov_b32_e32 v51, v1
	v_lshl_add_u64 v[14:15], v[14:15], 0, v[50:51]
	s_waitcnt vmcnt(0)
	flat_load_dword v18, v[14:15] offset:256
	flat_load_dword v19, v[14:15] offset:320
	v_lshlrev_b64 v[14:15], 7, v[58:59]
	v_lshl_add_u64 v[16:17], v[54:55], 0, v[14:15]
	v_lshl_add_u64 v[14:15], v[56:57], 0, v[14:15]
	flat_load_dwordx2 v[72:73], v[16:17]
	flat_load_dwordx2 v[74:75], v[14:15]
	v_mov_b64_e32 v[68:69], s[14:15]
	s_add_i32 s22, s22, s68
	s_waitcnt lgkmcnt(0)
	v_lshlrev_b32_e32 v20, 16, v2
	v_and_b32_e32 v21, 0xffff0000, v2
	v_lshlrev_b32_e32 v15, 16, v3
	v_and_b32_e32 v14, 0xffff0000, v3
	v_lshlrev_b32_e32 v3, 16, v4
	v_and_b32_e32 v2, 0xffff0000, v4
	v_lshlrev_b32_e32 v4, 16, v6
	v_and_b32_e32 v22, 0xffff0000, v6
	v_lshlrev_b32_e32 v17, 16, v7
	v_and_b32_e32 v16, 0xffff0000, v7
	v_lshlrev_b32_e32 v7, 16, v8
	v_and_b32_e32 v6, 0xffff0000, v8
	v_pk_mul_f32 v[6:7], v[6:7], v[6:7]
	v_mul_f32_e32 v8, v4, v4
	v_pk_fma_f32 v[2:3], v[2:3], v[2:3], v[6:7]
	v_and_b32_e32 v6, 0xffff0000, v9
	v_lshlrev_b32_e32 v7, 16, v9
	v_and_b32_e32 v4, 0xffff0000, v5
	v_lshlrev_b32_e32 v5, 16, v5
	v_pk_mul_f32 v[6:7], v[6:7], v[6:7]
	v_mul_f32_e32 v22, v22, v22
	v_pk_fma_f32 v[4:5], v[4:5], v[4:5], v[6:7]
	v_and_b32_e32 v7, 0xffff0000, v10
	v_lshlrev_b32_e32 v6, 16, v10
	v_mul_f32_e32 v9, v7, v7
	v_fmac_f32_e32 v9, v6, v6
	v_and_b32_e32 v6, 0xffff0000, v11
	v_lshlrev_b32_e32 v7, 16, v11
	v_pk_mul_f32 v[6:7], v[6:7], v[6:7]
	v_fmac_f32_e32 v22, v21, v21
	v_add_f32_e32 v7, v7, v9
	v_add_f32_e32 v9, v6, v7
	v_and_b32_e32 v6, 0xffff0000, v12
	v_lshlrev_b32_e32 v7, 16, v12
	v_pk_mul_f32 v[6:7], v[6:7], v[6:7]
	v_pk_mul_f32 v[16:17], v[16:17], v[16:17]
	v_add_f32_e32 v7, v7, v9
	v_add_f32_e32 v9, v6, v7
	v_and_b32_e32 v6, 0xffff0000, v13
	v_lshlrev_b32_e32 v7, 16, v13
	v_pk_mul_f32 v[6:7], v[6:7], v[6:7]
	v_fmac_f32_e32 v8, v20, v20
	v_add_f32_e32 v7, v7, v9
	v_pk_fma_f32 v[14:15], v[14:15], v[14:15], v[16:17]
	v_add_f32_e32 v6, v6, v7
	v_add_f32_e32 v7, v8, v22
	v_add_f32_e32 v7, v15, v7
	v_add_f32_e32 v7, v14, v7
	v_add_f32_e32 v3, v3, v7
	v_add_f32_e32 v2, v2, v3
	v_add_f32_e32 v2, v5, v2
	s_waitcnt vmcnt(0)
	v_and_b32_e32 v79, 0xffff0000, v19
	v_add_f32_e32 v3, v4, v2
	v_lshlrev_b32_e32 v78, 16, v19
	v_mul_f32_e32 v2, v79, v79
	v_pk_fma_f32 v[86:87], v[78:79], v[78:79], v[2:3] op_sel_hi:[1,1,0]
	v_lshlrev_b32_e32 v76, 16, v18
	v_add_f32_dpp v2, v3, v3 row_ror:1 row_mask:0xf bank_mask:0xf bound_ctrl:1
	v_add_f32_dpp v3, v6, v6 row_ror:1 row_mask:0xf bank_mask:0xf bound_ctrl:1
	v_and_b32_e32 v77, 0xffff0000, v18
	v_add_f32_dpp v2, v2, v2 row_ror:2 row_mask:0xf bank_mask:0xf bound_ctrl:1
	v_add_f32_dpp v3, v3, v3 row_ror:2 row_mask:0xf bank_mask:0xf bound_ctrl:1
	s_nop 0
	v_add_f32_dpp v2, v2, v2 row_ror:4 row_mask:0xf bank_mask:0xf bound_ctrl:1
	v_add_f32_dpp v3, v3, v3 row_ror:4 row_mask:0xf bank_mask:0xf bound_ctrl:1
	s_nop 0
	v_add_f32_dpp v2, v2, v2 row_ror:8 row_mask:0xf bank_mask:0xf bound_ctrl:1
	v_fmamk_f32 v2, v2, 0x3b800000, v228
	v_cmp_gt_f32_e64 s[0:1], s95, v2
	v_mul_f32_e32 v4, 0x4b800000, v2
	v_add_f32_dpp v3, v3, v3 row_ror:8 row_mask:0xf bank_mask:0xf bound_ctrl:1
	v_cndmask_b32_e64 v2, v2, v4, s[0:1]
	v_rsq_f32_e32 v6, v2
	v_fmamk_f32 v2, v3, 0x3c000000, v228
	v_cmp_gt_f32_e32 vcc, s95, v2
	v_mul_f32_e32 v3, 0x4b800000, v2
	v_lshlrev_b64 v[4:5], 11, v[58:59]
	v_cndmask_b32_e32 v2, v2, v3, vcc
	v_rsq_f32_e32 v87, v2
	v_mad_i64_i32 v[2:3], s[2:3], v58, s76, v[68:69]
	v_lshl_add_u64 v[84:85], v[2:3], 0, v[0:1]
	v_lshl_add_u64 v[70:71], v[2:3], 0, v[50:51]
	flat_load_dwordx4 v[94:97], v[84:85]
	flat_load_dword v59, v[70:71] offset:256
	flat_load_dword v111, v[70:71] offset:320
	v_lshl_add_u64 v[4:5], s[8:9], 0, v[4:5]
	v_mul_f32_e32 v7, 0x45800000, v6
	v_lshl_add_u64 v[2:3], v[4:5], 0, v[0:1]
	flat_load_dwordx4 v[38:41], v[2:3]
	flat_load_dwordx4 v[34:37], v[2:3] offset:256
	flat_load_dwordx4 v[98:101], v[84:85] offset:384
	flat_load_dword v133, v[70:71] offset:640
	flat_load_dword v134, v[70:71] offset:704
	flat_load_dwordx4 v[30:33], v[2:3] offset:512
	flat_load_dwordx4 v[26:29], v[2:3] offset:768
	flat_load_dwordx4 v[102:105], v[84:85] offset:768
	flat_load_dword v135, v[70:71] offset:1024
	flat_load_dword v136, v[70:71] offset:1088
	flat_load_dwordx4 v[22:25], v[2:3] offset:1024
	flat_load_dwordx4 v[18:21], v[2:3] offset:1280
	flat_load_dwordx4 v[106:109], v[84:85] offset:1152
	flat_load_dword v137, v[70:71] offset:1408
	flat_load_dword v138, v[70:71] offset:1472
	flat_load_dwordx4 v[14:17], v[2:3] offset:1536
	s_nop 0
	flat_load_dwordx4 v[2:5], v[2:3] offset:1792
	v_cndmask_b32_e64 v110, v6, v7, s[0:1]
	flat_load_dwordx4 v[46:49], v[66:67]
	flat_load_dwordx4 v[42:45], v[66:67] offset:16
	flat_load_dwordx4 v[10:13], v[64:65]
	flat_load_dwordx4 v[6:9], v[64:65] offset:16
	flat_load_dwordx2 v[90:91], v[62:63] offset:512
	flat_load_dwordx2 v[88:89], v[62:63] offset:640
	flat_load_dwordx2 v[82:83], v[60:61] offset:512
	flat_load_dwordx2 v[80:81], v[60:61] offset:640
	v_mul_f32_e32 v132, 0x45800000, v87
	s_waitcnt vmcnt(0) lgkmcnt(0)
; DI unsigned pk2(float lo, float hi) { f32x2 v = {lo, hi}; return __builtin_bit_cast(unsigned, __builtin_convertvector(v, bf2_t)); }
; DI float bflo(unsigned w) { return __uint_as_float(w << 16); }
; DI float bfhi(unsigned w) { return __uint_as_float(w & 0xffff0000u); }
; DI float red16(float v, int lane) { (void)lane; v += DPP_ROR(v, 1); v += DPP_ROR(v, 2); v += DPP_ROR(v, 4); v += DPP_ROR(v, 8); return v; }
; DI void unpack8(const u32x4 w, float (&v)[8]) { v[0] = bflo(w.x); v[1] = bfhi(w.x); v[2] = bflo(w.y); v[3] = bfhi(w.y); v[4] = bflo(w.z); v[5] = bfhi(w.z); v[6] = bflo(w.w); v[7] = bfhi(w.w); }
; DI void finalize_tile(const Params& p, int l, int tile, LAS unsigned char* lds, int tid, int lane, int wave, const bool doq = true) {
;     ...
;         if (doq)
; #pragma unroll
;         for (int h = 0; h < 4; ++h) {
;             bf16_t* qp = QR + t * 768 + h * 192;
;             const u32x4 qa = qa4[h]; const unsigned r1 = r14[h], r2 = r24[h];
;             unpack8(qa, v);
;             const float y1a = bflo(r1) * rcq, y1b = bfhi(r1) * rcq, y2a = bflo(r2) * rcq, y2b = bfhi(r2) * rcq;
;             float ss = (y1a * y1a + y1b * y1b) + (y2a * y2a + y2b * y2b);
; #pragma unroll
;             for (int e = 0; e < 8; ++e) { v[e] *= rcq; ss += v[e] * v[e]; }
;             ss = red16(ss, lane);
;             const float rq = rsqrtf(ss * (1.0f / 192.0f) + EPS) * QSCALE;
;             const f32x4 g0 = qg0, g1 = qg1; const f32x2 gr1 = qgr1, gr2 = qgr2;
;             u32x4 o; o.x = pk2(v[0] * rq * g0.x, v[1] * rq * g0.y); o.y = pk2(v[2] * rq * g0.z, v[3] * rq * g0.w); o.z = pk2(v[4] * rq * g1.x, v[5] * rq * g1.y); o.w = pk2(v[6] * rq * g1.z, v[7] * rq * g1.w);
;             *(u32x4*)(qp + 8 * i) = o;
;             const float a1 = y1a * rq * gr1.x, b1 = y1b * rq * gr1.y, a2 = y2a * rq * gr2.x, b2 = y2b * rq * gr2.y;
;             *(unsigned*)(qp + 128 + 2 * i) = pk2(a1 * cs.x - a2 * sn.x, b1 * cs.y - b2 * sn.y);
;             *(unsigned*)(qp + 160 + 2 * i) = pk2(a1 * sn.x + a2 * cs.x, b1 * sn.y + b2 * cs.y);
;         }
	v_lshlrev_b32_e32 v112, 16, v59
	v_and_b32_e32 v113, 0xffff0000, v59
	v_lshlrev_b32_e32 v114, 16, v111
	v_and_b32_e32 v115, 0xffff0000, v111
	v_pk_mul_f32 v[112:113], v[110:111], v[112:113] op_sel_hi:[0,1]
	v_pk_mul_f32 v[114:115], v[110:111], v[114:115] op_sel_hi:[0,1]
	v_lshlrev_b32_e32 v116, 16, v97
	v_and_b32_e32 v117, 0xffff0000, v97
	v_lshlrev_b32_e32 v120, 16, v96
	v_and_b32_e32 v121, 0xffff0000, v96
	v_lshlrev_b32_e32 v122, 16, v95
	v_and_b32_e32 v123, 0xffff0000, v95
	v_lshlrev_b32_e32 v126, 16, v94
	v_and_b32_e32 v127, 0xffff0000, v94
	v_pk_mul_f32 v[128:129], v[112:113], v[112:113]
	v_pk_mul_f32 v[130:131], v[114:115], v[114:115]
	v_pk_mul_f32 v[116:117], v[110:111], v[116:117] op_sel_hi:[0,1]
	v_pk_mul_f32 v[96:97], v[110:111], v[120:121] op_sel_hi:[0,1]
	v_pk_mul_f32 v[122:123], v[110:111], v[122:123] op_sel_hi:[0,1]
	v_pk_mul_f32 v[94:95], v[110:111], v[126:127] op_sel_hi:[0,1]
	v_add_f32_e32 v59, v130, v131
	v_add_f32_e32 v111, v128, v129
	v_pk_mul_f32 v[126:127], v[94:95], v[94:95]
	v_add_f32_e32 v59, v111, v59
	v_add_f32_e32 v59, v126, v59
	v_pk_mul_f32 v[124:125], v[122:123], v[122:123]
	v_add_f32_e32 v59, v127, v59
	v_add_f32_e32 v59, v124, v59
	v_pk_mul_f32 v[120:121], v[96:97], v[96:97]
	v_add_f32_e32 v59, v125, v59
	v_add_f32_e32 v59, v120, v59
	v_pk_mul_f32 v[118:119], v[116:117], v[116:117]
	v_add_f32_e32 v59, v121, v59
	v_add_f32_e32 v59, v118, v59
	v_add_f32_e32 v59, v119, v59
	s_nop 1
	v_add_f32_dpp v59, v59, v59 row_ror:1 row_mask:0xf bank_mask:0xf bound_ctrl:1
	s_nop 1
	v_add_f32_dpp v59, v59, v59 row_ror:2 row_mask:0xf bank_mask:0xf bound_ctrl:1
	s_nop 1
	v_add_f32_dpp v59, v59, v59 row_ror:4 row_mask:0xf bank_mask:0xf bound_ctrl:1
	s_nop 1
	v_add_f32_dpp v59, v59, v59 row_ror:8 row_mask:0xf bank_mask:0xf bound_ctrl:1
	v_fmamk_f32 v59, v59, 0x3baaaaab, v228
	v_cmp_gt_f32_e64 s[0:1], s95, v59
	v_mul_f32_e32 v111, 0x4b800000, v59
	s_nop 0
	v_cndmask_b32_e64 v59, v59, v111, s[0:1]
	v_rsq_f32_e32 v59, v59
	s_nop 0
	v_mul_f32_e32 v111, 0x45800000, v59
	v_cndmask_b32_e64 v59, v59, v111, s[0:1]
	v_mul_f32_e32 v118, 0x3dd53b94, v59
	v_pk_mul_f32 v[94:95], v[94:95], v[118:119] op_sel_hi:[1,0]
	v_pk_mul_f32 v[120:121], v[122:123], v[118:119] op_sel_hi:[1,0]
	v_pk_mul_f32 v[96:97], v[96:97], v[118:119] op_sel_hi:[1,0]
	v_pk_mul_f32 v[116:117], v[116:117], v[118:119] op_sel_hi:[1,0]
	v_pk_mul_f32 v[94:95], v[46:47], v[94:95]
	v_pk_mul_f32 v[120:121], v[48:49], v[120:121]
	v_pk_mul_f32 v[96:97], v[42:43], v[96:97]
	v_pk_mul_f32 v[116:117], v[44:45], v[116:117]
	v_cvt_pk_bf16_f32 v94, v94, v95
	v_cvt_pk_bf16_f32 v95, v120, v121
	v_cvt_pk_bf16_f32 v96, v96, v97
	v_cvt_pk_bf16_f32 v97, v116, v117
	flat_store_dwordx4 v[84:85], v[94:97]
	v_lshlrev_b32_e32 v122, 16, v98
	v_and_b32_e32 v123, 0xffff0000, v98
	v_pk_mul_f32 v[96:97], v[114:115], v[118:119] op_sel_hi:[1,0]
	v_pk_mul_f32 v[94:95], v[112:113], v[118:119] op_sel_hi:[1,0]
	v_pk_mul_f32 v[96:97], v[88:89], v[96:97]
	v_pk_mul_f32 v[94:95], v[90:91], v[94:95]
	v_pk_mul_f32 v[112:113], v[74:75], v[96:97]
	v_pk_mul_f32 v[96:97], v[72:73], v[96:97]
	v_pk_fma_f32 v[112:113], v[72:73], v[94:95], v[112:113] neg_lo:[0,0,1] neg_hi:[0,0,1]
	v_pk_fma_f32 v[94:95], v[74:75], v[94:95], v[96:97]
	v_cvt_pk_bf16_f32 v59, v112, v113
	flat_store_dword v[70:71], v59 offset:256
	v_cvt_pk_bf16_f32 v59, v94, v95
	v_lshlrev_b32_e32 v94, 16, v133
	v_and_b32_e32 v95, 0xffff0000, v133
	v_lshlrev_b32_e32 v96, 16, v134
	v_and_b32_e32 v97, 0xffff0000, v134
	v_pk_mul_f32 v[124:125], v[110:111], v[94:95] op_sel_hi:[0,1]
	v_pk_mul_f32 v[126:127], v[110:111], v[96:97] op_sel_hi:[0,1]
	v_pk_mul_f32 v[94:95], v[124:125], v[124:125]
	v_pk_mul_f32 v[96:97], v[126:127], v[126:127]
	flat_store_dword v[70:71], v59 offset:320
	v_lshlrev_b32_e32 v118, 16, v99
	v_and_b32_e32 v119, 0xffff0000, v99
	v_pk_mul_f32 v[98:99], v[110:111], v[122:123] op_sel_hi:[0,1]
	v_add_f32_e32 v59, v96, v97
	v_add_f32_e32 v94, v94, v95
	v_pk_mul_f32 v[122:123], v[98:99], v[98:99]
	v_add_f32_e32 v59, v94, v59
	v_pk_mul_f32 v[118:119], v[110:111], v[118:119] op_sel_hi:[0,1]
	v_add_f32_e32 v59, v122, v59
	v_lshlrev_b32_e32 v116, 16, v100
	v_and_b32_e32 v117, 0xffff0000, v100
	v_pk_mul_f32 v[120:121], v[118:119], v[118:119]
	v_add_f32_e32 v59, v123, v59
	v_lshlrev_b32_e32 v112, 16, v101
	v_and_b32_e32 v113, 0xffff0000, v101
	v_pk_mul_f32 v[100:101], v[110:111], v[116:117] op_sel_hi:[0,1]
	v_add_f32_e32 v59, v120, v59
	v_pk_mul_f32 v[116:117], v[100:101], v[100:101]
	v_add_f32_e32 v59, v121, v59
	v_pk_mul_f32 v[112:113], v[110:111], v[112:113] op_sel_hi:[0,1]
	v_add_f32_e32 v59, v116, v59
	v_pk_mul_f32 v[114:115], v[112:113], v[112:113]
	v_add_f32_e32 v59, v117, v59
	v_add_f32_e32 v59, v114, v59
	v_add_f32_e32 v59, v115, v59
	s_nop 1
	v_add_f32_dpp v59, v59, v59 row_ror:1 row_mask:0xf bank_mask:0xf bound_ctrl:1
	s_nop 1
	v_add_f32_dpp v59, v59, v59 row_ror:2 row_mask:0xf bank_mask:0xf bound_ctrl:1
	s_nop 1
	v_add_f32_dpp v59, v59, v59 row_ror:4 row_mask:0xf bank_mask:0xf bound_ctrl:1
	s_nop 1
	v_add_f32_dpp v59, v59, v59 row_ror:8 row_mask:0xf bank_mask:0xf bound_ctrl:1
	v_fmamk_f32 v59, v59, 0x3baaaaab, v228
	v_cmp_gt_f32_e64 s[0:1], s95, v59
	v_mul_f32_e32 v94, 0x4b800000, v59
	s_nop 0
	v_cndmask_b32_e64 v59, v59, v94, s[0:1]
	v_rsq_f32_e32 v59, v59
	s_nop 0
	v_mul_f32_e32 v94, 0x45800000, v59
	v_cndmask_b32_e64 v59, v59, v94, s[0:1]
	v_mul_f32_e32 v114, 0x3dd53b94, v59
	v_pk_mul_f32 v[94:95], v[98:99], v[114:115] op_sel_hi:[1,0]
	v_pk_mul_f32 v[96:97], v[118:119], v[114:115] op_sel_hi:[1,0]
	v_pk_mul_f32 v[94:95], v[46:47], v[94:95]
	v_pk_mul_f32 v[96:97], v[48:49], v[96:97]
	v_cvt_pk_bf16_f32 v94, v94, v95
	v_cvt_pk_bf16_f32 v95, v96, v97
; DI unsigned pk2(float lo, float hi) { f32x2 v = {lo, hi}; return __builtin_bit_cast(unsigned, __builtin_convertvector(v, bf2_t)); }
; DI float bflo(unsigned w) { return __uint_as_float(w << 16); }
; DI float bfhi(unsigned w) { return __uint_as_float(w & 0xffff0000u); }
; DI float red16(float v, int lane) { (void)lane; v += DPP_ROR(v, 1); v += DPP_ROR(v, 2); v += DPP_ROR(v, 4); v += DPP_ROR(v, 8); return v; }
; DI void unpack8(const u32x4 w, float (&v)[8]) { v[0] = bflo(w.x); v[1] = bfhi(w.x); v[2] = bflo(w.y); v[3] = bfhi(w.y); v[4] = bflo(w.z); v[5] = bfhi(w.z); v[6] = bflo(w.w); v[7] = bfhi(w.w); }
; DI void finalize_tile(const Params& p, int l, int tile, LAS unsigned char* lds, int tid, int lane, int wave, const bool doq = true) {
;     ...
;         if (doq)
; #pragma unroll
;         for (int h = 0; h < 4; ++h) {
;             bf16_t* qp = QR + t * 768 + h * 192;
;             const u32x4 qa = qa4[h]; const unsigned r1 = r14[h], r2 = r24[h];
;             unpack8(qa, v);
;             const float y1a = bflo(r1) * rcq, y1b = bfhi(r1) * rcq, y2a = bflo(r2) * rcq, y2b = bfhi(r2) * rcq;
;             float ss = (y1a * y1a + y1b * y1b) + (y2a * y2a + y2b * y2b);
; #pragma unroll
;             for (int e = 0; e < 8; ++e) { v[e] *= rcq; ss += v[e] * v[e]; }
;             ss = red16(ss, lane);
;             const float rq = rsqrtf(ss * (1.0f / 192.0f) + EPS) * QSCALE;
;             const f32x4 g0 = qg0, g1 = qg1; const f32x2 gr1 = qgr1, gr2 = qgr2;
;             u32x4 o; o.x = pk2(v[0] * rq * g0.x, v[1] * rq * g0.y); o.y = pk2(v[2] * rq * g0.z, v[3] * rq * g0.w); o.z = pk2(v[4] * rq * g1.x, v[5] * rq * g1.y); o.w = pk2(v[6] * rq * g1.z, v[7] * rq * g1.w);
;             *(u32x4*)(qp + 8 * i) = o;
;             const float a1 = y1a * rq * gr1.x, b1 = y1b * rq * gr1.y, a2 = y2a * rq * gr2.x, b2 = y2b * rq * gr2.y;
;             *(unsigned*)(qp + 128 + 2 * i) = pk2(a1 * cs.x - a2 * sn.x, b1 * cs.y - b2 * sn.y);
;             *(unsigned*)(qp + 160 + 2 * i) = pk2(a1 * sn.x + a2 * cs.x, b1 * sn.y + b2 * cs.y);
;         }
	v_pk_mul_f32 v[96:97], v[100:101], v[114:115] op_sel_hi:[1,0]
	v_pk_mul_f32 v[98:99], v[112:113], v[114:115] op_sel_hi:[1,0]
	v_pk_mul_f32 v[96:97], v[42:43], v[96:97]
	v_pk_mul_f32 v[98:99], v[44:45], v[98:99]
	v_cvt_pk_bf16_f32 v96, v96, v97
	v_cvt_pk_bf16_f32 v97, v98, v99
	flat_store_dwordx4 v[84:85], v[94:97] offset:384
	v_lshlrev_b32_e32 v118, 16, v102
	v_and_b32_e32 v119, 0xffff0000, v102
	v_pk_mul_f32 v[96:97], v[126:127], v[114:115] op_sel_hi:[1,0]
	v_pk_mul_f32 v[94:95], v[124:125], v[114:115] op_sel_hi:[1,0]
	v_pk_mul_f32 v[96:97], v[88:89], v[96:97]
	v_pk_mul_f32 v[94:95], v[90:91], v[94:95]
	v_pk_mul_f32 v[98:99], v[74:75], v[96:97]
	v_pk_mul_f32 v[96:97], v[72:73], v[96:97]
	v_pk_fma_f32 v[98:99], v[72:73], v[94:95], v[98:99] neg_lo:[0,0,1] neg_hi:[0,0,1]
	v_pk_fma_f32 v[94:95], v[74:75], v[94:95], v[96:97]
	v_cvt_pk_bf16_f32 v59, v98, v99
	flat_store_dword v[70:71], v59 offset:640
	v_cvt_pk_bf16_f32 v59, v94, v95
	v_lshlrev_b32_e32 v94, 16, v135
	v_and_b32_e32 v95, 0xffff0000, v135
	v_lshlrev_b32_e32 v96, 16, v136
	v_and_b32_e32 v97, 0xffff0000, v136
	v_pk_mul_f32 v[120:121], v[110:111], v[94:95] op_sel_hi:[0,1]
	v_pk_mul_f32 v[122:123], v[110:111], v[96:97] op_sel_hi:[0,1]
	v_pk_mul_f32 v[94:95], v[120:121], v[120:121]
	v_pk_mul_f32 v[96:97], v[122:123], v[122:123]
	flat_store_dword v[70:71], v59 offset:704
	v_lshlrev_b32_e32 v114, 16, v103
	v_and_b32_e32 v115, 0xffff0000, v103
	v_pk_mul_f32 v[102:103], v[110:111], v[118:119] op_sel_hi:[0,1]
	v_add_f32_e32 v59, v96, v97
	v_add_f32_e32 v94, v94, v95
	v_pk_mul_f32 v[118:119], v[102:103], v[102:103]
	v_add_f32_e32 v59, v94, v59
	v_pk_mul_f32 v[114:115], v[110:111], v[114:115] op_sel_hi:[0,1]
	v_add_f32_e32 v59, v118, v59
	v_lshlrev_b32_e32 v112, 16, v104
	v_and_b32_e32 v113, 0xffff0000, v104
	v_pk_mul_f32 v[116:117], v[114:115], v[114:115]
	v_add_f32_e32 v59, v119, v59
	v_lshlrev_b32_e32 v98, 16, v105
	v_and_b32_e32 v99, 0xffff0000, v105
	v_pk_mul_f32 v[104:105], v[110:111], v[112:113] op_sel_hi:[0,1]
	v_add_f32_e32 v59, v116, v59
	v_pk_mul_f32 v[112:113], v[104:105], v[104:105]
	v_add_f32_e32 v59, v117, v59
	v_pk_mul_f32 v[98:99], v[110:111], v[98:99] op_sel_hi:[0,1]
	v_add_f32_e32 v59, v112, v59
	v_pk_mul_f32 v[100:101], v[98:99], v[98:99]
	v_add_f32_e32 v59, v113, v59
	v_add_f32_e32 v59, v100, v59
	v_add_f32_e32 v59, v101, v59
	s_nop 1
	v_add_f32_dpp v59, v59, v59 row_ror:1 row_mask:0xf bank_mask:0xf bound_ctrl:1
	s_nop 1
	v_add_f32_dpp v59, v59, v59 row_ror:2 row_mask:0xf bank_mask:0xf bound_ctrl:1
	s_nop 1
	v_add_f32_dpp v59, v59, v59 row_ror:4 row_mask:0xf bank_mask:0xf bound_ctrl:1
	s_nop 1
	v_add_f32_dpp v59, v59, v59 row_ror:8 row_mask:0xf bank_mask:0xf bound_ctrl:1
	v_fmamk_f32 v59, v59, 0x3baaaaab, v228
	v_cmp_gt_f32_e64 s[0:1], s95, v59
	v_mul_f32_e32 v94, 0x4b800000, v59
	s_nop 0
	v_cndmask_b32_e64 v59, v59, v94, s[0:1]
	v_rsq_f32_e32 v59, v59
	s_nop 0
	v_mul_f32_e32 v94, 0x45800000, v59
	v_cndmask_b32_e64 v59, v59, v94, s[0:1]
	v_mul_f32_e32 v100, 0x3dd53b94, v59
	v_pk_mul_f32 v[94:95], v[102:103], v[100:101] op_sel_hi:[1,0]
	v_pk_mul_f32 v[96:97], v[114:115], v[100:101] op_sel_hi:[1,0]
	v_pk_mul_f32 v[94:95], v[46:47], v[94:95]
	v_pk_mul_f32 v[96:97], v[48:49], v[96:97]
	v_cvt_pk_bf16_f32 v94, v94, v95
	v_cvt_pk_bf16_f32 v95, v96, v97
	v_pk_mul_f32 v[96:97], v[104:105], v[100:101] op_sel_hi:[1,0]
	v_pk_mul_f32 v[98:99], v[98:99], v[100:101] op_sel_hi:[1,0]
	v_pk_mul_f32 v[96:97], v[42:43], v[96:97]
	v_pk_mul_f32 v[98:99], v[44:45], v[98:99]
	v_cvt_pk_bf16_f32 v96, v96, v97
	v_cvt_pk_bf16_f32 v97, v98, v99
	flat_store_dwordx4 v[84:85], v[94:97] offset:768
	v_lshlrev_b32_e32 v102, 16, v108
	v_and_b32_e32 v103, 0xffff0000, v108
	v_pk_mul_f32 v[96:97], v[122:123], v[100:101] op_sel_hi:[1,0]
	v_pk_mul_f32 v[94:95], v[120:121], v[100:101] op_sel_hi:[1,0]
	v_pk_mul_f32 v[96:97], v[88:89], v[96:97]
	v_pk_mul_f32 v[94:95], v[90:91], v[94:95]
	v_pk_mul_f32 v[98:99], v[74:75], v[96:97]
	v_pk_mul_f32 v[96:97], v[72:73], v[96:97]
	v_pk_fma_f32 v[98:99], v[72:73], v[94:95], v[98:99] neg_lo:[0,0,1] neg_hi:[0,0,1]
	v_pk_fma_f32 v[94:95], v[74:75], v[94:95], v[96:97]
	v_cvt_pk_bf16_f32 v59, v98, v99
	flat_store_dword v[70:71], v59 offset:1024
	v_cvt_pk_bf16_f32 v59, v94, v95
	v_lshlrev_b32_e32 v94, 16, v137
	v_and_b32_e32 v95, 0xffff0000, v137
	v_lshlrev_b32_e32 v96, 16, v138
	v_and_b32_e32 v97, 0xffff0000, v138
	v_lshlrev_b32_e32 v98, 16, v109
	v_and_b32_e32 v99, 0xffff0000, v109
	v_lshlrev_b32_e32 v108, 16, v107
	v_and_b32_e32 v109, 0xffff0000, v107
	v_lshlrev_b32_e32 v114, 16, v106
	v_and_b32_e32 v115, 0xffff0000, v106
	v_pk_mul_f32 v[94:95], v[110:111], v[94:95] op_sel_hi:[0,1]
	v_pk_mul_f32 v[96:97], v[110:111], v[96:97] op_sel_hi:[0,1]
	v_pk_mul_f32 v[98:99], v[110:111], v[98:99] op_sel_hi:[0,1]
	v_pk_mul_f32 v[102:103], v[110:111], v[102:103] op_sel_hi:[0,1]
	v_pk_mul_f32 v[108:109], v[110:111], v[108:109] op_sel_hi:[0,1]
	v_pk_mul_f32 v[106:107], v[110:111], v[114:115] op_sel_hi:[0,1]
	v_pk_mul_f32 v[110:111], v[94:95], v[94:95]
	v_pk_mul_f32 v[116:117], v[96:97], v[96:97]
	flat_store_dword v[70:71], v59 offset:1088
	v_add_f32_e32 v59, v116, v117
	v_add_f32_e32 v110, v110, v111
	v_pk_mul_f32 v[114:115], v[106:107], v[106:107]
	v_add_f32_e32 v59, v110, v59
	v_add_f32_e32 v59, v114, v59
	v_pk_mul_f32 v[112:113], v[108:109], v[108:109]
	v_add_f32_e32 v59, v115, v59
	v_add_f32_e32 v59, v112, v59
	v_pk_mul_f32 v[104:105], v[102:103], v[102:103]
	v_add_f32_e32 v59, v113, v59
	v_add_f32_e32 v59, v104, v59
	v_pk_mul_f32 v[100:101], v[98:99], v[98:99]
	v_add_f32_e32 v59, v105, v59
	v_add_f32_e32 v59, v100, v59
	v_add_f32_e32 v59, v101, v59
	s_nop 1
; DI void finalize_tile(const Params& p, int l, int tile, LAS unsigned char* lds, int tid, int lane, int wave, const bool doq = true) {
;     ...
;         for (int h = 0; h < 4; ++h) {
;             bf16_t* qp = QR + t * 768 + h * 192;
;             const u32x4 qa = qa4[h]; const unsigned r1 = r14[h], r2 = r24[h];
;             unpack8(qa, v);
;             const float y1a = bflo(r1) * rcq, y1b = bfhi(r1) * rcq, y2a = bflo(r2) * rcq, y2b = bfhi(r2) * rcq;
;             float ss = (y1a * y1a + y1b * y1b) + (y2a * y2a + y2b * y2b);
; #pragma unroll
;             for (int e = 0; e < 8; ++e) { v[e] *= rcq; ss += v[e] * v[e]; }
;             ss = red16(ss, lane);
;             const float rq = rsqrtf(ss * (1.0f / 192.0f) + EPS) * QSCALE;
;             const f32x4 g0 = qg0, g1 = qg1; const f32x2 gr1 = qgr1, gr2 = qgr2;
;             u32x4 o; o.x = pk2(v[0] * rq * g0.x, v[1] * rq * g0.y); o.y = pk2(v[2] * rq * g0.z, v[3] * rq * g0.w); o.z = pk2(v[4] * rq * g1.x, v[5] * rq * g1.y); o.w = pk2(v[6] * rq * g1.z, v[7] * rq * g1.w);
;             *(u32x4*)(qp + 8 * i) = o;
;             const float a1 = y1a * rq * gr1.x, b1 = y1b * rq * gr1.y, a2 = y2a * rq * gr2.x, b2 = y2b * rq * gr2.y;
;             *(unsigned*)(qp + 128 + 2 * i) = pk2(a1 * cs.x - a2 * sn.x, b1 * cs.y - b2 * sn.y);
;             *(unsigned*)(qp + 160 + 2 * i) = pk2(a1 * sn.x + a2 * cs.x, b1 * sn.y + b2 * cs.y);
;         }
; #pragma unroll
;         for (int h = 0; h < 4; ++h) {
;             const u32x4 ka = ka4[h], va = va4[h];
;             unpack8(ka, v);
;             float ss = 0.f;
; #pragma unroll
;             for (int e = 0; e < 8; ++e) { v[e] *= rckv; ss += v[e] * v[e]; }
;             ss = red16(ss, lane) + s3;
;             const float rk = rsqrtf(ss * (1.0f / 192.0f) + EPS);
;             const f32x4 g0 = kg0, g1 = kg1; const f32x2 gr1 = kgr1, gr2 = kgr2;
;             bf16_t* ko = KB + t * 768 + h * 192;
;             u32x4 o; o.x = pk2(v[0] * rk * g0.x, v[1] * rk * g0.y); o.y = pk2(v[2] * rk * g0.z, v[3] * rk * g0.w); o.z = pk2(v[4] * rk * g1.x, v[5] * rk * g1.y); o.w = pk2(v[6] * rk * g1.z, v[7] * rk * g1.w);
;             *(u32x4*)(ko + 8 * i) = o;
;             const float a1 = x1a * rk * gr1.x, b1 = x1b * rk * gr1.y, a2 = x2a * rk * gr2.x, b2 = x2b * rk * gr2.y;
;             *(unsigned*)(ko + 128 + 2 * i) = pk2(a1 * cs.x - a2 * sn.x, b1 * cs.y - b2 * sn.y);
	v_add_f32_dpp v59, v59, v59 row_ror:1 row_mask:0xf bank_mask:0xf bound_ctrl:1
	s_nop 1
	v_add_f32_dpp v59, v59, v59 row_ror:2 row_mask:0xf bank_mask:0xf bound_ctrl:1
	s_nop 1
	v_add_f32_dpp v59, v59, v59 row_ror:4 row_mask:0xf bank_mask:0xf bound_ctrl:1
	s_nop 1
	v_add_f32_dpp v59, v59, v59 row_ror:8 row_mask:0xf bank_mask:0xf bound_ctrl:1
	v_fmamk_f32 v59, v59, 0x3baaaaab, v228
	v_cmp_gt_f32_e64 s[0:1], s95, v59
	v_mul_f32_e32 v100, 0x4b800000, v59
	s_nop 0
	v_cndmask_b32_e64 v59, v59, v100, s[0:1]
	v_rsq_f32_e32 v59, v59
	s_nop 0
	v_mul_f32_e32 v100, 0x45800000, v59
	v_cndmask_b32_e64 v59, v59, v100, s[0:1]
	v_mul_f32_e32 v100, 0x3dd53b94, v59
	v_pk_mul_f32 v[104:105], v[106:107], v[100:101] op_sel_hi:[1,0]
	s_nop 0
	v_pk_mul_f32 v[46:47], v[46:47], v[104:105]
	v_pk_mul_f32 v[104:105], v[108:109], v[100:101] op_sel_hi:[1,0]
	v_cvt_pk_bf16_f32 v46, v46, v47
	v_pk_mul_f32 v[48:49], v[48:49], v[104:105]
	s_nop 0
	v_cvt_pk_bf16_f32 v47, v48, v49
	v_pk_mul_f32 v[48:49], v[102:103], v[100:101] op_sel_hi:[1,0]
	s_nop 0
	v_pk_mul_f32 v[42:43], v[42:43], v[48:49]
	s_nop 0
	v_cvt_pk_bf16_f32 v48, v42, v43
	v_pk_mul_f32 v[42:43], v[98:99], v[100:101] op_sel_hi:[1,0]
	s_nop 0
	v_pk_mul_f32 v[42:43], v[44:45], v[42:43]
	v_pk_mul_f32 v[44:45], v[96:97], v[100:101] op_sel_hi:[1,0]
	v_cvt_pk_bf16_f32 v49, v42, v43
	v_pk_mul_f32 v[42:43], v[94:95], v[100:101] op_sel_hi:[1,0]
	v_pk_mul_f32 v[44:45], v[88:89], v[44:45]
	flat_store_dwordx4 v[84:85], v[46:49] offset:1152
	v_pk_mul_f32 v[42:43], v[90:91], v[42:43]
	v_lshlrev_b32_e32 v84, 16, v38
	v_pk_mul_f32 v[46:47], v[74:75], v[44:45]
	v_pk_mul_f32 v[44:45], v[72:73], v[44:45]
	v_pk_fma_f32 v[46:47], v[72:73], v[42:43], v[46:47] neg_lo:[0,0,1] neg_hi:[0,0,1]
	v_pk_fma_f32 v[42:43], v[74:75], v[42:43], v[44:45]
	v_cvt_pk_bf16_f32 v46, v46, v47
	v_cvt_pk_bf16_f32 v42, v42, v43
	flat_store_dword v[70:71], v42 offset:1472
	v_cndmask_b32_e32 v42, v87, v132, vcc
	v_lshlrev_b32_e32 v43, 10, v93
	v_lshlrev_b32_e32 v48, 16, v40
	v_and_b32_e32 v49, 0xffff0000, v40
	v_and_b32_e32 v85, 0xffff0000, v38
	flat_store_dword v[70:71], v46 offset:1408
	v_lshlrev_b32_e32 v46, 16, v41
	v_and_b32_e32 v47, 0xffff0000, v41
	v_pk_mul_f32 v[40:41], v[42:43], v[48:49] op_sel_hi:[0,1]
	v_lshlrev_b32_e32 v48, 16, v39
	v_and_b32_e32 v49, 0xffff0000, v39
	v_pk_mul_f32 v[84:85], v[42:43], v[84:85] op_sel_hi:[0,1]
	v_pk_mul_f32 v[48:49], v[42:43], v[48:49] op_sel_hi:[0,1]
	v_pk_mul_f32 v[38:39], v[84:85], v[84:85]
	v_pk_mul_f32 v[94:95], v[48:49], v[48:49]
	v_add_f32_e32 v38, v38, v39
	v_add_f32_e32 v38, v94, v38
	v_pk_mul_f32 v[46:47], v[42:43], v[46:47] op_sel_hi:[0,1]
	v_add_f32_e32 v38, v95, v38
	v_pk_mul_f32 v[90:91], v[46:47], v[46:47]
	v_fmac_f32_e32 v38, v40, v40
	v_pk_fma_f32 v[94:95], v[40:41], v[40:41], v[38:39] op_sel_hi:[1,1,0]
	v_mov_b32_e32 v87, v91
	v_pk_mul_f32 v[90:91], v[76:77], v[76:77]
	v_mov_b32_e32 v96, v76
	v_mov_b32_e32 v97, v46
	v_mov_b32_e32 v94, v91
	v_pk_fma_f32 v[90:91], v[96:97], v[96:97], v[94:95]
	v_add3_u32 v88, 0, v0, v43
	v_pk_add_f32 v[86:87], v[90:91], v[86:87]
	v_mov_b32_e32 v90, v1
	v_mov_b32_e32 v91, v1
	v_mov_b64_e32 v[70:71], s[12:13]
	v_mov_b32_dpp v90, v86 row_ror:1 row_mask:0xf bank_mask:0xf
	v_mov_b32_dpp v91, v87 row_ror:1 row_mask:0xf bank_mask:0xf
	v_pk_add_f32 v[86:87], v[86:87], v[90:91]
	v_mov_b32_e32 v90, v1
	v_mov_b32_e32 v91, v1
	v_mad_i64_i32 v[44:45], s[0:1], v58, s76, v[70:71]
	v_mov_b32_dpp v90, v86 row_ror:2 row_mask:0xf bank_mask:0xf
	v_mov_b32_dpp v91, v87 row_ror:2 row_mask:0xf bank_mask:0xf
	v_pk_add_f32 v[86:87], v[86:87], v[90:91]
	v_mov_b32_e32 v90, v1
	v_mov_b32_e32 v91, v1
	v_lshl_add_u64 v[38:39], v[44:45], 0, v[0:1]
	v_mov_b32_dpp v90, v86 row_ror:4 row_mask:0xf bank_mask:0xf
	v_mov_b32_dpp v91, v87 row_ror:4 row_mask:0xf bank_mask:0xf
	v_pk_add_f32 v[86:87], v[86:87], v[90:91]
	v_mov_b32_e32 v90, v1
	v_mov_b32_e32 v91, v1
	v_lshl_add_u64 v[44:45], v[44:45], 0, v[50:51]
	v_mov_b32_dpp v90, v86 row_ror:8 row_mask:0xf bank_mask:0xf
	v_mov_b32_dpp v91, v87 row_ror:8 row_mask:0xf bank_mask:0xf
	v_pk_add_f32 v[90:91], v[86:87], v[90:91]
	s_nop 0
	v_add_f32_e32 v43, v90, v91
	v_fmamk_f32 v43, v43, 0x3baaaaab, v228
	v_cmp_gt_f32_e32 vcc, s95, v43
	v_mul_f32_e32 v59, 0x4b800000, v43
	s_nop 0
	v_cndmask_b32_e32 v43, v43, v59, vcc
	v_rsq_f32_e32 v43, v43
	s_nop 0
	v_mul_f32_e32 v59, 0x45800000, v43
	v_cndmask_b32_e32 v94, v43, v59, vcc
	v_pk_mul_f32 v[40:41], v[40:41], v[94:95] op_sel_hi:[1,0]
	v_pk_mul_f32 v[84:85], v[84:85], v[94:95] op_sel_hi:[1,0]
	v_pk_mul_f32 v[40:41], v[6:7], v[40:41]
	v_pk_mul_f32 v[48:49], v[48:49], v[94:95] op_sel_hi:[1,0]
	v_cvt_pk_bf16_f32 v86, v40, v41
	v_pk_mul_f32 v[40:41], v[46:47], v[94:95] op_sel_hi:[1,0]
	v_pk_mul_f32 v[46:47], v[94:95], v[78:79] op_sel_hi:[0,1]
	v_pk_mul_f32 v[40:41], v[8:9], v[40:41]
	v_pk_mul_f32 v[84:85], v[10:11], v[84:85]
	v_pk_mul_f32 v[48:49], v[12:13], v[48:49]
	v_cvt_pk_bf16_f32 v87, v40, v41
	v_pk_mul_f32 v[40:41], v[94:95], v[76:77] op_sel_hi:[0,1]
	v_pk_mul_f32 v[46:47], v[80:81], v[46:47]
	v_cvt_pk_bf16_f32 v84, v84, v85
	v_cvt_pk_bf16_f32 v85, v48, v49
	v_pk_mul_f32 v[40:41], v[82:83], v[40:41]
	v_pk_mul_f32 v[48:49], v[74:75], v[46:47]
	v_pk_mul_f32 v[46:47], v[72:73], v[46:47]
	v_pk_fma_f32 v[48:49], v[72:73], v[40:41], v[48:49] neg_lo:[0,0,1] neg_hi:[0,0,1]
	v_pk_fma_f32 v[40:41], v[74:75], v[40:41], v[46:47]
	v_cvt_pk_bf16_f32 v43, v48, v49
	v_cvt_pk_bf16_f32 v40, v40, v41
	flat_store_dword v[44:45], v40 offset:320
	v_lshlrev_b32_e32 v40, 16, v34
	v_and_b32_e32 v41, 0xffff0000, v34
	v_pk_mul_f32 v[40:41], v[42:43], v[40:41] op_sel_hi:[0,1]
	v_cvt_pk_bf16_f32 v34, v40, v41
	v_lshlrev_b32_e32 v40, 16, v35
; #define LAS __attribute__((address_space(3)))
; DI unsigned pk2(float lo, float hi) { f32x2 v = {lo, hi}; return __builtin_bit_cast(unsigned, __builtin_convertvector(v, bf2_t)); }
; DI float red16(float v, int lane) { (void)lane; v += DPP_ROR(v, 1); v += DPP_ROR(v, 2); v += DPP_ROR(v, 4); v += DPP_ROR(v, 8); return v; }
; DI void unpack8(const u32x4 w, float (&v)[8]) { v[0] = bflo(w.x); v[1] = bfhi(w.x); v[2] = bflo(w.y); v[3] = bfhi(w.y); v[4] = bflo(w.z); v[5] = bfhi(w.z); v[6] = bflo(w.w); v[7] = bfhi(w.w); }
; DI void finalize_tile(const Params& p, int l, int tile, LAS unsigned char* lds, int tid, int lane, int wave, const bool doq = true) {
;     ...
; #pragma unroll
;         for (int h = 0; h < 4; ++h) {
;             const u32x4 ka = ka4[h], va = va4[h];
;             unpack8(ka, v);
;             float ss = 0.f;
; #pragma unroll
;             for (int e = 0; e < 8; ++e) { v[e] *= rckv; ss += v[e] * v[e]; }
;             ss = red16(ss, lane) + s3;
;             const float rk = rsqrtf(ss * (1.0f / 192.0f) + EPS);
;             const f32x4 g0 = kg0, g1 = kg1; const f32x2 gr1 = kgr1, gr2 = kgr2;
;             bf16_t* ko = KB + t * 768 + h * 192;
;             u32x4 o; o.x = pk2(v[0] * rk * g0.x, v[1] * rk * g0.y); o.y = pk2(v[2] * rk * g0.z, v[3] * rk * g0.w); o.z = pk2(v[4] * rk * g1.x, v[5] * rk * g1.y); o.w = pk2(v[6] * rk * g1.z, v[7] * rk * g1.w);
;             *(u32x4*)(ko + 8 * i) = o;
;             const float a1 = x1a * rk * gr1.x, b1 = x1b * rk * gr1.y, a2 = x2a * rk * gr2.x, b2 = x2b * rk * gr2.y;
;             *(unsigned*)(ko + 128 + 2 * i) = pk2(a1 * cs.x - a2 * sn.x, b1 * cs.y - b2 * sn.y);
;             *(unsigned*)(ko + 160 + 2 * i) = pk2(a1 * sn.x + a2 * cs.x, b1 * sn.y + b2 * cs.y);
;             unpack8(va, w);
;             u32x4 vo; vo.x = pk2(w[0] * rckv, w[1] * rckv); vo.y = pk2(w[2] * rckv, w[3] * rckv); vo.z = pk2(w[4] * rckv, w[5] * rckv); vo.w = pk2(w[6] * rckv, w[7] * rckv);
;             *(LAS u32x4*)(VL + tl * 512 + h * 128 + 8 * i) = vo;
;         }
	v_and_b32_e32 v41, 0xffff0000, v35
	v_pk_mul_f32 v[40:41], v[42:43], v[40:41] op_sel_hi:[0,1]
	v_cvt_pk_bf16_f32 v35, v40, v41
	v_lshlrev_b32_e32 v40, 16, v36
	v_and_b32_e32 v41, 0xffff0000, v36
	v_pk_mul_f32 v[40:41], v[42:43], v[40:41] op_sel_hi:[0,1]
	v_cvt_pk_bf16_f32 v36, v40, v41
	v_lshlrev_b32_e32 v40, 16, v37
	v_and_b32_e32 v41, 0xffff0000, v37
	flat_store_dwordx4 v[38:39], v[84:87]
	v_pk_mul_f32 v[40:41], v[42:43], v[40:41] op_sel_hi:[0,1]
	v_cvt_pk_bf16_f32 v37, v40, v41
	v_lshlrev_b32_e32 v84, 16, v30
	v_and_b32_e32 v85, 0xffff0000, v30
	v_lshlrev_b32_e32 v46, 16, v31
	v_and_b32_e32 v47, 0xffff0000, v31
	v_pk_mul_f32 v[30:31], v[42:43], v[84:85] op_sel_hi:[0,1]
	flat_store_dword v[44:45], v43 offset:256
	ds_write_b128 v88, v[34:37]
	v_lshlrev_b32_e32 v34, 16, v33
	v_and_b32_e32 v35, 0xffff0000, v33
	v_lshlrev_b32_e32 v40, 16, v32
	v_and_b32_e32 v41, 0xffff0000, v32
	v_pk_mul_f32 v[46:47], v[42:43], v[46:47] op_sel_hi:[0,1]
	v_pk_mul_f32 v[84:85], v[30:31], v[30:31]
	v_pk_mul_f32 v[34:35], v[42:43], v[34:35] op_sel_hi:[0,1]
	v_pk_mul_f32 v[32:33], v[42:43], v[40:41] op_sel_hi:[0,1]
	v_pk_mul_f32 v[48:49], v[46:47], v[46:47]
	v_add_f32_e32 v43, v84, v85
	v_add_f32_e32 v43, v48, v43
	v_pk_mul_f32 v[40:41], v[32:33], v[32:33]
	v_add_f32_e32 v43, v49, v43
	v_add_f32_e32 v40, v40, v43
	v_pk_mul_f32 v[36:37], v[34:35], v[34:35]
	v_add_f32_e32 v40, v41, v40
	v_add_f32_e32 v36, v36, v40
	v_add_f32_e32 v36, v37, v36
	s_nop 1
	v_add_f32_dpp v36, v36, v36 row_ror:1 row_mask:0xf bank_mask:0xf bound_ctrl:1
	s_nop 1
	v_add_f32_dpp v36, v36, v36 row_ror:2 row_mask:0xf bank_mask:0xf bound_ctrl:1
	s_nop 1
	v_add_f32_dpp v36, v36, v36 row_ror:4 row_mask:0xf bank_mask:0xf bound_ctrl:1
	s_nop 1
	v_add_f32_dpp v36, v36, v36 row_ror:8 row_mask:0xf bank_mask:0xf bound_ctrl:1
	v_add_f32_e32 v36, v90, v36
	v_fmamk_f32 v36, v36, 0x3baaaaab, v228
	v_cmp_gt_f32_e32 vcc, s95, v36
	v_mul_f32_e32 v37, 0x4b800000, v36
	s_nop 0
	v_cndmask_b32_e32 v36, v36, v37, vcc
	v_rsq_f32_e32 v36, v36
	s_nop 0
	v_mul_f32_e32 v37, 0x45800000, v36
	v_cndmask_b32_e32 v36, v36, v37, vcc
	v_pk_mul_f32 v[30:31], v[30:31], v[36:37] op_sel_hi:[1,0]
	v_pk_mul_f32 v[40:41], v[46:47], v[36:37] op_sel_hi:[1,0]
	v_pk_mul_f32 v[32:33], v[32:33], v[36:37] op_sel_hi:[1,0]
	v_pk_mul_f32 v[34:35], v[34:35], v[36:37] op_sel_hi:[1,0]
	v_pk_mul_f32 v[30:31], v[10:11], v[30:31]
	v_pk_mul_f32 v[40:41], v[12:13], v[40:41]
	v_pk_mul_f32 v[32:33], v[6:7], v[32:33]
	v_pk_mul_f32 v[34:35], v[8:9], v[34:35]
	v_cvt_pk_bf16_f32 v30, v30, v31
	v_cvt_pk_bf16_f32 v31, v40, v41
	v_cvt_pk_bf16_f32 v32, v32, v33
	v_cvt_pk_bf16_f32 v33, v34, v35
	flat_store_dwordx4 v[38:39], v[30:33] offset:384
	s_nop 1
	v_pk_mul_f32 v[32:33], v[36:37], v[78:79] op_sel_hi:[0,1]
	v_pk_mul_f32 v[30:31], v[36:37], v[76:77] op_sel_hi:[0,1]
	v_pk_mul_f32 v[32:33], v[80:81], v[32:33]
	v_pk_mul_f32 v[30:31], v[82:83], v[30:31]
	v_pk_mul_f32 v[34:35], v[74:75], v[32:33]
	v_pk_mul_f32 v[32:33], v[72:73], v[32:33]
	v_pk_fma_f32 v[34:35], v[72:73], v[30:31], v[34:35] neg_lo:[0,0,1] neg_hi:[0,0,1]
	v_pk_fma_f32 v[30:31], v[74:75], v[30:31], v[32:33]
	v_lshlrev_b32_e32 v36, 16, v22
	v_cvt_pk_bf16_f32 v30, v30, v31
	flat_store_dword v[44:45], v30 offset:704
	v_lshlrev_b32_e32 v30, 16, v26
	v_and_b32_e32 v31, 0xffff0000, v26
	v_pk_mul_f32 v[30:31], v[42:43], v[30:31] op_sel_hi:[0,1]
	v_cvt_pk_bf16_f32 v26, v30, v31
	v_lshlrev_b32_e32 v30, 16, v27
	v_and_b32_e32 v31, 0xffff0000, v27
	v_pk_mul_f32 v[30:31], v[42:43], v[30:31] op_sel_hi:[0,1]
	v_cvt_pk_bf16_f32 v27, v30, v31
	v_lshlrev_b32_e32 v30, 16, v28
	v_and_b32_e32 v31, 0xffff0000, v28
	v_pk_mul_f32 v[30:31], v[42:43], v[30:31] op_sel_hi:[0,1]
	v_and_b32_e32 v37, 0xffff0000, v22
	v_cvt_pk_bf16_f32 v28, v30, v31
	v_lshlrev_b32_e32 v30, 16, v29
	v_and_b32_e32 v31, 0xffff0000, v29
	v_lshlrev_b32_e32 v32, 16, v23
	v_and_b32_e32 v33, 0xffff0000, v23
	v_pk_mul_f32 v[22:23], v[42:43], v[36:37] op_sel_hi:[0,1]
	v_cvt_pk_bf16_f32 v34, v34, v35
	v_pk_mul_f32 v[30:31], v[42:43], v[30:31] op_sel_hi:[0,1]
	v_pk_mul_f32 v[32:33], v[42:43], v[32:33] op_sel_hi:[0,1]
	v_pk_mul_f32 v[36:37], v[22:23], v[22:23]
	flat_store_dword v[44:45], v34 offset:640
	v_cvt_pk_bf16_f32 v29, v30, v31
	v_lshlrev_b32_e32 v30, 16, v24
	v_and_b32_e32 v31, 0xffff0000, v24
	v_pk_mul_f32 v[34:35], v[32:33], v[32:33]
	v_add_f32_e32 v36, v36, v37
	ds_write_b128 v88, v[26:29] offset:256
	v_lshlrev_b32_e32 v26, 16, v25
	v_and_b32_e32 v27, 0xffff0000, v25
	v_pk_mul_f32 v[24:25], v[42:43], v[30:31] op_sel_hi:[0,1]
	v_add_f32_e32 v34, v34, v36
	v_pk_mul_f32 v[30:31], v[24:25], v[24:25]
	v_add_f32_e32 v34, v35, v34
	v_pk_mul_f32 v[26:27], v[42:43], v[26:27] op_sel_hi:[0,1]
	v_add_f32_e32 v30, v30, v34
	v_pk_mul_f32 v[28:29], v[26:27], v[26:27]
	v_add_f32_e32 v30, v31, v30
	v_add_f32_e32 v28, v28, v30
	v_add_f32_e32 v28, v29, v28
	s_nop 1
	v_add_f32_dpp v28, v28, v28 row_ror:1 row_mask:0xf bank_mask:0xf bound_ctrl:1
	s_nop 1
	v_add_f32_dpp v28, v28, v28 row_ror:2 row_mask:0xf bank_mask:0xf bound_ctrl:1
	s_nop 1
	v_add_f32_dpp v28, v28, v28 row_ror:4 row_mask:0xf bank_mask:0xf bound_ctrl:1
	s_nop 1
	v_add_f32_dpp v28, v28, v28 row_ror:8 row_mask:0xf bank_mask:0xf bound_ctrl:1
	v_add_f32_e32 v28, v90, v28
	v_fmamk_f32 v28, v28, 0x3baaaaab, v228
	v_cmp_gt_f32_e32 vcc, s95, v28
	v_mul_f32_e32 v29, 0x4b800000, v28
	s_nop 0
	v_cndmask_b32_e32 v28, v28, v29, vcc
	v_rsq_f32_e32 v28, v28
	s_nop 0
	v_mul_f32_e32 v29, 0x45800000, v28
	v_cndmask_b32_e32 v28, v28, v29, vcc
	v_pk_mul_f32 v[22:23], v[22:23], v[28:29] op_sel_hi:[1,0]
	v_pk_mul_f32 v[30:31], v[32:33], v[28:29] op_sel_hi:[1,0]
	v_pk_mul_f32 v[24:25], v[24:25], v[28:29] op_sel_hi:[1,0]
; #define LAS __attribute__((address_space(3)))
; DI unsigned pk2(float lo, float hi) { f32x2 v = {lo, hi}; return __builtin_bit_cast(unsigned, __builtin_convertvector(v, bf2_t)); }
; DI void finalize_tile(const Params& p, int l, int tile, LAS unsigned char* lds, int tid, int lane, int wave, const bool doq = true) {
;     ...
;         const int tl = wave * 8 + it * 4 + sub; const size_t t = (size_t)(t0 + tl);
;         const u32x4 c0 = *(const u32x4*)(CQ + t * 256 + 16 * i), c1 = *(const u32x4*)(CQ + t * 256 + 16 * i + 8);
;         const u32x4 kvw = *(const u32x4*)(MISC + t * 256 + 8 * i);
;         const unsigned p1 = *(const unsigned*)(MISC + t * 256 + 128 + 2 * i), p2 = *(const unsigned*)(MISC + t * 256 + 160 + 2 * i);
;         const f32x2 cs = *(const f32x2*)(COS + t * 32 + 2 * i), sn = *(const f32x2*)(SIN + t * 32 + 2 * i);
;         float v[8], w[8]; float s1 = 0.f, s2 = 0.f;
;         unpack8(c0, v); unpack8(c1, w);
;     ...
; #pragma unroll
;         for (int h = 0; h < 4; ++h) {
;             const u32x4 ka = ka4[h], va = va4[h];
;             unpack8(ka, v);
;             float ss = 0.f;
; #pragma unroll
;             for (int e = 0; e < 8; ++e) { v[e] *= rckv; ss += v[e] * v[e]; }
;             ss = red16(ss, lane) + s3;
;             const float rk = rsqrtf(ss * (1.0f / 192.0f) + EPS);
;             const f32x4 g0 = kg0, g1 = kg1; const f32x2 gr1 = kgr1, gr2 = kgr2;
;             bf16_t* ko = KB + t * 768 + h * 192;
;             u32x4 o; o.x = pk2(v[0] * rk * g0.x, v[1] * rk * g0.y); o.y = pk2(v[2] * rk * g0.z, v[3] * rk * g0.w); o.z = pk2(v[4] * rk * g1.x, v[5] * rk * g1.y); o.w = pk2(v[6] * rk * g1.z, v[7] * rk * g1.w);
;             *(u32x4*)(ko + 8 * i) = o;
;             const float a1 = x1a * rk * gr1.x, b1 = x1b * rk * gr1.y, a2 = x2a * rk * gr2.x, b2 = x2b * rk * gr2.y;
;             *(unsigned*)(ko + 128 + 2 * i) = pk2(a1 * cs.x - a2 * sn.x, b1 * cs.y - b2 * sn.y);
;             *(unsigned*)(ko + 160 + 2 * i) = pk2(a1 * sn.x + a2 * cs.x, b1 * sn.y + b2 * cs.y);
;             unpack8(va, w);
;             u32x4 vo; vo.x = pk2(w[0] * rckv, w[1] * rckv); vo.y = pk2(w[2] * rckv, w[3] * rckv); vo.z = pk2(w[4] * rckv, w[5] * rckv); vo.w = pk2(w[6] * rckv, w[7] * rckv);
;             *(LAS u32x4*)(VL + tl * 512 + h * 128 + 8 * i) = vo;
;         }
	v_pk_mul_f32 v[26:27], v[26:27], v[28:29] op_sel_hi:[1,0]
	v_pk_mul_f32 v[22:23], v[10:11], v[22:23]
	v_pk_mul_f32 v[30:31], v[12:13], v[30:31]
	v_pk_mul_f32 v[24:25], v[6:7], v[24:25]
	v_pk_mul_f32 v[26:27], v[8:9], v[26:27]
	v_cvt_pk_bf16_f32 v22, v22, v23
	v_cvt_pk_bf16_f32 v23, v30, v31
	v_cvt_pk_bf16_f32 v24, v24, v25
	v_cvt_pk_bf16_f32 v25, v26, v27
	flat_store_dwordx4 v[38:39], v[22:25] offset:768
	s_nop 1
	v_pk_mul_f32 v[24:25], v[28:29], v[78:79] op_sel_hi:[0,1]
	v_pk_mul_f32 v[22:23], v[28:29], v[76:77] op_sel_hi:[0,1]
	v_pk_mul_f32 v[24:25], v[80:81], v[24:25]
	v_pk_mul_f32 v[22:23], v[82:83], v[22:23]
	v_pk_mul_f32 v[26:27], v[74:75], v[24:25]
	v_pk_mul_f32 v[24:25], v[72:73], v[24:25]
	v_pk_fma_f32 v[26:27], v[72:73], v[22:23], v[26:27] neg_lo:[0,0,1] neg_hi:[0,0,1]
	v_pk_fma_f32 v[22:23], v[74:75], v[22:23], v[24:25]
	v_lshlrev_b32_e32 v28, 16, v14
	v_cvt_pk_bf16_f32 v22, v22, v23
	flat_store_dword v[44:45], v22 offset:1088
	v_lshlrev_b32_e32 v22, 16, v18
	v_and_b32_e32 v23, 0xffff0000, v18
	v_pk_mul_f32 v[22:23], v[42:43], v[22:23] op_sel_hi:[0,1]
	v_cvt_pk_bf16_f32 v18, v22, v23
	v_lshlrev_b32_e32 v22, 16, v19
	v_and_b32_e32 v23, 0xffff0000, v19
	v_pk_mul_f32 v[22:23], v[42:43], v[22:23] op_sel_hi:[0,1]
	v_cvt_pk_bf16_f32 v19, v22, v23
	v_lshlrev_b32_e32 v22, 16, v20
	v_and_b32_e32 v23, 0xffff0000, v20
	v_pk_mul_f32 v[22:23], v[42:43], v[22:23] op_sel_hi:[0,1]
	v_and_b32_e32 v29, 0xffff0000, v14
	v_cvt_pk_bf16_f32 v20, v22, v23
	v_lshlrev_b32_e32 v22, 16, v21
	v_and_b32_e32 v23, 0xffff0000, v21
	v_lshlrev_b32_e32 v24, 16, v15
	v_and_b32_e32 v25, 0xffff0000, v15
	v_pk_mul_f32 v[14:15], v[42:43], v[28:29] op_sel_hi:[0,1]
	v_cvt_pk_bf16_f32 v26, v26, v27
	v_pk_mul_f32 v[22:23], v[42:43], v[22:23] op_sel_hi:[0,1]
	v_pk_mul_f32 v[24:25], v[42:43], v[24:25] op_sel_hi:[0,1]
	v_pk_mul_f32 v[28:29], v[14:15], v[14:15]
	flat_store_dword v[44:45], v26 offset:1024
	v_cvt_pk_bf16_f32 v21, v22, v23
	v_lshlrev_b32_e32 v22, 16, v16
	v_and_b32_e32 v23, 0xffff0000, v16
	v_pk_mul_f32 v[26:27], v[24:25], v[24:25]
	v_add_f32_e32 v28, v28, v29
	ds_write_b128 v88, v[18:21] offset:512
	v_lshlrev_b32_e32 v18, 16, v17
	v_and_b32_e32 v19, 0xffff0000, v17
	v_pk_mul_f32 v[16:17], v[42:43], v[22:23] op_sel_hi:[0,1]
	v_add_f32_e32 v26, v26, v28
	v_pk_mul_f32 v[22:23], v[16:17], v[16:17]
	v_add_f32_e32 v26, v27, v26
	v_pk_mul_f32 v[18:19], v[42:43], v[18:19] op_sel_hi:[0,1]
	v_add_f32_e32 v22, v22, v26
	v_pk_mul_f32 v[20:21], v[18:19], v[18:19]
	v_add_f32_e32 v22, v23, v22
	v_add_f32_e32 v20, v20, v22
	v_add_f32_e32 v20, v21, v20
	s_nop 1
	v_add_f32_dpp v20, v20, v20 row_ror:1 row_mask:0xf bank_mask:0xf bound_ctrl:1
	s_nop 1
	v_add_f32_dpp v20, v20, v20 row_ror:2 row_mask:0xf bank_mask:0xf bound_ctrl:1
	s_nop 1
	v_add_f32_dpp v20, v20, v20 row_ror:4 row_mask:0xf bank_mask:0xf bound_ctrl:1
	s_nop 1
	v_add_f32_dpp v20, v20, v20 row_ror:8 row_mask:0xf bank_mask:0xf bound_ctrl:1
	v_add_f32_e32 v20, v90, v20
	v_fmamk_f32 v20, v20, 0x3baaaaab, v228
	v_cmp_gt_f32_e32 vcc, s95, v20
	v_mul_f32_e32 v21, 0x4b800000, v20
	s_nop 0
	v_cndmask_b32_e32 v20, v20, v21, vcc
	v_rsq_f32_e32 v20, v20
	s_nop 0
	v_mul_f32_e32 v21, 0x45800000, v20
	v_cndmask_b32_e32 v20, v20, v21, vcc
	v_pk_mul_f32 v[14:15], v[14:15], v[20:21] op_sel_hi:[1,0]
	s_nop 0
	v_pk_mul_f32 v[10:11], v[10:11], v[14:15]
	v_pk_mul_f32 v[14:15], v[24:25], v[20:21] op_sel_hi:[1,0]
	v_cvt_pk_bf16_f32 v10, v10, v11
	v_pk_mul_f32 v[12:13], v[12:13], v[14:15]
	s_nop 0
	v_cvt_pk_bf16_f32 v11, v12, v13
	v_pk_mul_f32 v[12:13], v[16:17], v[20:21] op_sel_hi:[1,0]
	s_nop 0
	v_pk_mul_f32 v[6:7], v[6:7], v[12:13]
	s_nop 0
	v_cvt_pk_bf16_f32 v12, v6, v7
	v_pk_mul_f32 v[6:7], v[18:19], v[20:21] op_sel_hi:[1,0]
	s_nop 0
	v_pk_mul_f32 v[6:7], v[8:9], v[6:7]
	v_pk_mul_f32 v[8:9], v[20:21], v[78:79] op_sel_hi:[0,1]
	v_cvt_pk_bf16_f32 v13, v6, v7
	v_pk_mul_f32 v[6:7], v[20:21], v[76:77] op_sel_hi:[0,1]
	v_pk_mul_f32 v[8:9], v[80:81], v[8:9]
	flat_store_dwordx4 v[38:39], v[10:13] offset:1152
	v_pk_mul_f32 v[6:7], v[82:83], v[6:7]
	s_nop 0
	v_pk_mul_f32 v[10:11], v[74:75], v[8:9]
	v_pk_mul_f32 v[8:9], v[72:73], v[8:9]
	v_pk_fma_f32 v[10:11], v[72:73], v[6:7], v[10:11] neg_lo:[0,0,1] neg_hi:[0,0,1]
	v_pk_fma_f32 v[6:7], v[74:75], v[6:7], v[8:9]
	v_add_u32_e32 v72, 4, v58
	v_cvt_pk_bf16_f32 v6, v6, v7
	flat_store_dword v[44:45], v6 offset:1472
	v_lshlrev_b32_e32 v6, 16, v2
	v_and_b32_e32 v7, 0xffff0000, v2
	v_pk_mul_f32 v[6:7], v[42:43], v[6:7] op_sel_hi:[0,1]
	v_cvt_pk_bf16_f32 v2, v6, v7
	v_lshlrev_b32_e32 v6, 16, v3
	v_and_b32_e32 v7, 0xffff0000, v3
	v_pk_mul_f32 v[6:7], v[42:43], v[6:7] op_sel_hi:[0,1]
	v_cvt_pk_bf16_f32 v3, v6, v7
	v_lshlrev_b32_e32 v6, 16, v4
	v_and_b32_e32 v7, 0xffff0000, v4
	v_pk_mul_f32 v[6:7], v[42:43], v[6:7] op_sel_hi:[0,1]
	v_cvt_pk_bf16_f32 v4, v6, v7
	v_lshlrev_b32_e32 v6, 16, v5
	v_and_b32_e32 v7, 0xffff0000, v5
	v_cvt_pk_bf16_f32 v10, v10, v11
	v_pk_mul_f32 v[6:7], v[42:43], v[6:7] op_sel_hi:[0,1]
	v_ashrrev_i32_e32 v73, 31, v72
	flat_store_dword v[44:45], v10 offset:1408
	v_cvt_pk_bf16_f32 v5, v6, v7
	v_lshlrev_b64 v[10:11], 9, v[72:73]
	ds_write_b128 v88, v[2:5] offset:768
	v_lshl_add_u64 v[6:7], v[52:53], 0, v[10:11]
	flat_load_dwordx4 v[2:5], v[6:7]
	s_nop 0
	flat_load_dwordx4 v[6:9], v[6:7] offset:16
	v_lshl_add_u64 v[14:15], s[10:11], 0, v[10:11]
	v_lshl_add_u64 v[10:11], v[14:15], 0, v[0:1]
	flat_load_dwordx4 v[10:13], v[10:11]
	v_lshl_add_u64 v[14:15], v[14:15], 0, v[50:51]
	flat_load_dword v18, v[14:15] offset:256
	flat_load_dword v19, v[14:15] offset:320
	v_lshlrev_b64 v[14:15], 7, v[72:73]
	v_lshl_add_u64 v[16:17], v[54:55], 0, v[14:15]
	v_lshl_add_u64 v[14:15], v[56:57], 0, v[14:15]
	flat_load_dwordx2 v[52:53], v[16:17]
	flat_load_dwordx2 v[54:55], v[14:15]
	s_waitcnt vmcnt(0) lgkmcnt(0)
; DI float bflo(unsigned w) { return __uint_as_float(w << 16); }
; DI float bfhi(unsigned w) { return __uint_as_float(w & 0xffff0000u); }
; DI float red16(float v, int lane) { (void)lane; v += DPP_ROR(v, 1); v += DPP_ROR(v, 2); v += DPP_ROR(v, 4); v += DPP_ROR(v, 8); return v; }
; DI void finalize_tile(const Params& p, int l, int tile, LAS unsigned char* lds, int tid, int lane, int wave, const bool doq = true) {
;     ...
;         const int tl = wave * 8 + it * 4 + sub; const size_t t = (size_t)(t0 + tl);
;         const u32x4 c0 = *(const u32x4*)(CQ + t * 256 + 16 * i), c1 = *(const u32x4*)(CQ + t * 256 + 16 * i + 8);
;         const u32x4 kvw = *(const u32x4*)(MISC + t * 256 + 8 * i);
;         const unsigned p1 = *(const unsigned*)(MISC + t * 256 + 128 + 2 * i), p2 = *(const unsigned*)(MISC + t * 256 + 160 + 2 * i);
;         const f32x2 cs = *(const f32x2*)(COS + t * 32 + 2 * i), sn = *(const f32x2*)(SIN + t * 32 + 2 * i);
;         float v[8], w[8]; float s1 = 0.f, s2 = 0.f;
;         unpack8(c0, v); unpack8(c1, w);
; #pragma unroll
;         for (int e = 0; e < 8; ++e) s1 += v[e] * v[e] + w[e] * w[e];
;         unpack8(kvw, v);
; #pragma unroll
;         for (int e = 0; e < 8; ++e) s2 += v[e] * v[e];
;         const float x1a = bflo(p1), x1b = bfhi(p1), x2a = bflo(p2), x2b = bfhi(p2);
;         float s3 = (x1a * x1a + x1b * x1b) + (x2a * x2a + x2b * x2b);
;         s1 = red16(s1, lane); s2 = red16(s2, lane); s3 = red16(s3, lane);
;         const float rcq = rsqrtf(s1 * (1.0f / 256.0f) + EPS), rckv = rsqrtf(s2 * (1.0f / 128.0f) + EPS);
;         u32x4 qa4[4], ka4[4], va4[4]; unsigned r14[4], r24[4];
; #pragma unroll
;         for (int h = 0; h < 4; ++h) { const bf16_t* qp = QR + t * 768 + h * 192; const bf16_t* kp = KVR + t * 1024 + h * 256;
;             qa4[h] = *(const u32x4*)(qp + 8 * i); r14[h] = *(const unsigned*)(qp + 128 + 2 * i); r24[h] = *(const unsigned*)(qp + 160 + 2 * i);
;             ka4[h] = *(const u32x4*)(kp + 8 * i); va4[h] = *(const u32x4*)(kp + 128 + 8 * i); }
;         const f32x4 qg0 = *(const f32x4*)(qg + 8 * i), qg1 = *(const f32x4*)(qg + 8 * i + 4), kg0 = *(const f32x4*)(kg + 8 * i), kg1 = *(const f32x4*)(kg + 8 * i + 4);
;         const f32x2 qgr1 = *(const f32x2*)(qg + 128 + 2 * i), qgr2 = *(const f32x2*)(qg + 160 + 2 * i), kgr1 = *(const f32x2*)(kg + 128 + 2 * i), kgr2 = *(const f32x2*)(kg + 160 + 2 * i);
	v_lshlrev_b32_e32 v20, 16, v2
	v_and_b32_e32 v21, 0xffff0000, v2
	v_lshlrev_b32_e32 v15, 16, v3
	v_and_b32_e32 v14, 0xffff0000, v3
	v_lshlrev_b32_e32 v3, 16, v4
	v_and_b32_e32 v2, 0xffff0000, v4
	v_lshlrev_b32_e32 v4, 16, v6
	v_and_b32_e32 v22, 0xffff0000, v6
	v_lshlrev_b32_e32 v17, 16, v7
	v_and_b32_e32 v16, 0xffff0000, v7
	v_lshlrev_b32_e32 v7, 16, v8
	v_and_b32_e32 v6, 0xffff0000, v8
	v_pk_mul_f32 v[6:7], v[6:7], v[6:7]
	v_mul_f32_e32 v8, v4, v4
	v_pk_fma_f32 v[2:3], v[2:3], v[2:3], v[6:7]
	v_and_b32_e32 v6, 0xffff0000, v9
	v_lshlrev_b32_e32 v7, 16, v9
	v_and_b32_e32 v4, 0xffff0000, v5
	v_lshlrev_b32_e32 v5, 16, v5
	v_pk_mul_f32 v[6:7], v[6:7], v[6:7]
	v_mul_f32_e32 v22, v22, v22
	v_pk_fma_f32 v[4:5], v[4:5], v[4:5], v[6:7]
	v_and_b32_e32 v7, 0xffff0000, v10
	v_lshlrev_b32_e32 v6, 16, v10
	v_mul_f32_e32 v9, v7, v7
	v_fmac_f32_e32 v9, v6, v6
	v_and_b32_e32 v6, 0xffff0000, v11
	v_lshlrev_b32_e32 v7, 16, v11
	v_pk_mul_f32 v[6:7], v[6:7], v[6:7]
	v_fmac_f32_e32 v22, v21, v21
	v_add_f32_e32 v7, v7, v9
	v_add_f32_e32 v9, v6, v7
	v_and_b32_e32 v6, 0xffff0000, v12
	v_lshlrev_b32_e32 v7, 16, v12
	v_pk_mul_f32 v[6:7], v[6:7], v[6:7]
	v_pk_mul_f32 v[16:17], v[16:17], v[16:17]
	v_add_f32_e32 v7, v7, v9
	v_add_f32_e32 v9, v6, v7
	v_and_b32_e32 v6, 0xffff0000, v13
	v_lshlrev_b32_e32 v7, 16, v13
	v_pk_mul_f32 v[6:7], v[6:7], v[6:7]
	v_fmac_f32_e32 v8, v20, v20
	v_add_f32_e32 v7, v7, v9
	v_pk_fma_f32 v[14:15], v[14:15], v[14:15], v[16:17]
	v_add_f32_e32 v6, v6, v7
	v_add_f32_e32 v7, v8, v22
	v_add_f32_e32 v7, v15, v7
	v_add_f32_e32 v7, v14, v7
	v_add_f32_e32 v3, v3, v7
	v_add_f32_e32 v2, v2, v3
	v_add_f32_e32 v2, v5, v2
	v_and_b32_e32 v59, 0xffff0000, v19
	v_add_f32_e32 v3, v4, v2
	v_lshlrev_b32_e32 v58, 16, v19
	v_mul_f32_e32 v2, v59, v59
	v_pk_fma_f32 v[74:75], v[58:59], v[58:59], v[2:3] op_sel_hi:[1,1,0]
	v_lshlrev_b32_e32 v56, 16, v18
	v_add_f32_dpp v2, v3, v3 row_ror:1 row_mask:0xf bank_mask:0xf bound_ctrl:1
	v_add_f32_dpp v3, v6, v6 row_ror:1 row_mask:0xf bank_mask:0xf bound_ctrl:1
	v_and_b32_e32 v57, 0xffff0000, v18
	v_add_f32_dpp v2, v2, v2 row_ror:2 row_mask:0xf bank_mask:0xf bound_ctrl:1
	v_add_f32_dpp v3, v3, v3 row_ror:2 row_mask:0xf bank_mask:0xf bound_ctrl:1
	s_nop 0
	v_add_f32_dpp v2, v2, v2 row_ror:4 row_mask:0xf bank_mask:0xf bound_ctrl:1
	v_add_f32_dpp v3, v3, v3 row_ror:4 row_mask:0xf bank_mask:0xf bound_ctrl:1
	s_nop 0
	v_add_f32_dpp v2, v2, v2 row_ror:8 row_mask:0xf bank_mask:0xf bound_ctrl:1
	v_fmamk_f32 v2, v2, 0x3b800000, v228
	v_cmp_gt_f32_e64 s[0:1], s95, v2
	v_mul_f32_e32 v4, 0x4b800000, v2
	v_add_f32_dpp v3, v3, v3 row_ror:8 row_mask:0xf bank_mask:0xf bound_ctrl:1
	v_cndmask_b32_e64 v2, v2, v4, s[0:1]
	v_rsq_f32_e32 v6, v2
	v_fmamk_f32 v2, v3, 0x3c000000, v228
	v_cmp_gt_f32_e32 vcc, s95, v2
	v_mul_f32_e32 v3, 0x4b800000, v2
	v_lshlrev_b64 v[4:5], 11, v[72:73]
	v_cndmask_b32_e32 v2, v2, v3, vcc
	v_rsq_f32_e32 v75, v2
	v_mad_i64_i32 v[2:3], s[2:3], v72, s76, v[68:69]
	v_lshl_add_u64 v[76:77], v[2:3], 0, v[0:1]
	v_lshl_add_u64 v[68:69], v[2:3], 0, v[50:51]
	flat_load_dwordx4 v[78:81], v[76:77]
	flat_load_dword v73, v[68:69] offset:256
	flat_load_dword v87, v[68:69] offset:320
	v_lshl_add_u64 v[4:5], s[8:9], 0, v[4:5]
	v_mul_f32_e32 v7, 0x45800000, v6
	v_lshl_add_u64 v[2:3], v[4:5], 0, v[0:1]
	flat_load_dwordx4 v[38:41], v[2:3]
	flat_load_dwordx4 v[34:37], v[2:3] offset:256
	flat_load_dwordx4 v[82:85], v[76:77] offset:384
	flat_load_dword v93, v[68:69] offset:640
	flat_load_dword v120, v[68:69] offset:704
	flat_load_dwordx4 v[30:33], v[2:3] offset:512
	flat_load_dwordx4 v[26:29], v[2:3] offset:768
	flat_load_dwordx4 v[94:97], v[76:77] offset:768
	flat_load_dword v121, v[68:69] offset:1024
	flat_load_dword v122, v[68:69] offset:1088
	flat_load_dwordx4 v[22:25], v[2:3] offset:1024
	flat_load_dwordx4 v[18:21], v[2:3] offset:1280
	flat_load_dwordx4 v[98:101], v[76:77] offset:1152
	flat_load_dword v123, v[68:69] offset:1408
	flat_load_dword v124, v[68:69] offset:1472
	flat_load_dwordx4 v[14:17], v[2:3] offset:1536
	s_nop 0
	flat_load_dwordx4 v[2:5], v[2:3] offset:1792
	v_cndmask_b32_e64 v86, v6, v7, s[0:1]
	flat_load_dwordx4 v[46:49], v[66:67]
	flat_load_dwordx4 v[42:45], v[66:67] offset:16
	flat_load_dwordx4 v[10:13], v[64:65]
	flat_load_dwordx4 v[6:9], v[64:65] offset:16
	s_nop 0
	flat_load_dwordx2 v[66:67], v[62:63] offset:512
	flat_load_dwordx2 v[64:65], v[62:63] offset:640
	s_nop 0
	flat_load_dwordx2 v[62:63], v[60:61] offset:512
	s_nop 0
	flat_load_dwordx2 v[60:61], v[60:61] offset:640
	v_mul_f32_e32 v89, 0x45800000, v75
	s_waitcnt vmcnt(0) lgkmcnt(0)
; DI unsigned pk2(float lo, float hi) { f32x2 v = {lo, hi}; return __builtin_bit_cast(unsigned, __builtin_convertvector(v, bf2_t)); }
; DI float bflo(unsigned w) { return __uint_as_float(w << 16); }
; DI float bfhi(unsigned w) { return __uint_as_float(w & 0xffff0000u); }
; DI float red16(float v, int lane) { (void)lane; v += DPP_ROR(v, 1); v += DPP_ROR(v, 2); v += DPP_ROR(v, 4); v += DPP_ROR(v, 8); return v; }
; DI void unpack8(const u32x4 w, float (&v)[8]) { v[0] = bflo(w.x); v[1] = bfhi(w.x); v[2] = bflo(w.y); v[3] = bfhi(w.y); v[4] = bflo(w.z); v[5] = bfhi(w.z); v[6] = bflo(w.w); v[7] = bfhi(w.w); }
; DI void finalize_tile(const Params& p, int l, int tile, LAS unsigned char* lds, int tid, int lane, int wave, const bool doq = true) {
;     ...
;         if (doq)
; #pragma unroll
;         for (int h = 0; h < 4; ++h) {
;             bf16_t* qp = QR + t * 768 + h * 192;
;             const u32x4 qa = qa4[h]; const unsigned r1 = r14[h], r2 = r24[h];
;             unpack8(qa, v);
;             const float y1a = bflo(r1) * rcq, y1b = bfhi(r1) * rcq, y2a = bflo(r2) * rcq, y2b = bfhi(r2) * rcq;
;             float ss = (y1a * y1a + y1b * y1b) + (y2a * y2a + y2b * y2b);
; #pragma unroll
;             for (int e = 0; e < 8; ++e) { v[e] *= rcq; ss += v[e] * v[e]; }
;             ss = red16(ss, lane);
;             const float rq = rsqrtf(ss * (1.0f / 192.0f) + EPS) * QSCALE;
;             const f32x4 g0 = qg0, g1 = qg1; const f32x2 gr1 = qgr1, gr2 = qgr2;
;             u32x4 o; o.x = pk2(v[0] * rq * g0.x, v[1] * rq * g0.y); o.y = pk2(v[2] * rq * g0.z, v[3] * rq * g0.w); o.z = pk2(v[4] * rq * g1.x, v[5] * rq * g1.y); o.w = pk2(v[6] * rq * g1.z, v[7] * rq * g1.w);
;             *(u32x4*)(qp + 8 * i) = o;
;             const float a1 = y1a * rq * gr1.x, b1 = y1b * rq * gr1.y, a2 = y2a * rq * gr2.x, b2 = y2b * rq * gr2.y;
;             *(unsigned*)(qp + 128 + 2 * i) = pk2(a1 * cs.x - a2 * sn.x, b1 * cs.y - b2 * sn.y);
;             *(unsigned*)(qp + 160 + 2 * i) = pk2(a1 * sn.x + a2 * cs.x, b1 * sn.y + b2 * cs.y);
;         }
	v_lshlrev_b32_e32 v90, 16, v73
	v_and_b32_e32 v91, 0xffff0000, v73
	v_lshlrev_b32_e32 v102, 16, v87
	v_and_b32_e32 v103, 0xffff0000, v87
	v_pk_mul_f32 v[90:91], v[86:87], v[90:91] op_sel_hi:[0,1]
	v_pk_mul_f32 v[102:103], v[86:87], v[102:103] op_sel_hi:[0,1]
	v_lshlrev_b32_e32 v104, 16, v81
	v_and_b32_e32 v105, 0xffff0000, v81
	v_lshlrev_b32_e32 v108, 16, v80
	v_and_b32_e32 v109, 0xffff0000, v80
	v_lshlrev_b32_e32 v110, 16, v79
	v_and_b32_e32 v111, 0xffff0000, v79
	v_lshlrev_b32_e32 v114, 16, v78
	v_and_b32_e32 v115, 0xffff0000, v78
	v_pk_mul_f32 v[116:117], v[90:91], v[90:91]
	v_pk_mul_f32 v[118:119], v[102:103], v[102:103]
	v_pk_mul_f32 v[104:105], v[86:87], v[104:105] op_sel_hi:[0,1]
	v_pk_mul_f32 v[80:81], v[86:87], v[108:109] op_sel_hi:[0,1]
	v_pk_mul_f32 v[110:111], v[86:87], v[110:111] op_sel_hi:[0,1]
	v_pk_mul_f32 v[78:79], v[86:87], v[114:115] op_sel_hi:[0,1]
	v_add_f32_e32 v73, v118, v119
	v_add_f32_e32 v87, v116, v117
	v_pk_mul_f32 v[114:115], v[78:79], v[78:79]
	v_add_f32_e32 v73, v87, v73
	v_add_f32_e32 v73, v114, v73
	v_pk_mul_f32 v[112:113], v[110:111], v[110:111]
	v_add_f32_e32 v73, v115, v73
	v_add_f32_e32 v73, v112, v73
	v_pk_mul_f32 v[108:109], v[80:81], v[80:81]
	v_add_f32_e32 v73, v113, v73
	v_add_f32_e32 v73, v108, v73
	v_pk_mul_f32 v[106:107], v[104:105], v[104:105]
	v_add_f32_e32 v73, v109, v73
	v_add_f32_e32 v73, v106, v73
	v_add_f32_e32 v73, v107, v73
	s_nop 1
	v_add_f32_dpp v73, v73, v73 row_ror:1 row_mask:0xf bank_mask:0xf bound_ctrl:1
	s_nop 1
	v_add_f32_dpp v73, v73, v73 row_ror:2 row_mask:0xf bank_mask:0xf bound_ctrl:1
	s_nop 1
	v_add_f32_dpp v73, v73, v73 row_ror:4 row_mask:0xf bank_mask:0xf bound_ctrl:1
	s_nop 1
	v_add_f32_dpp v73, v73, v73 row_ror:8 row_mask:0xf bank_mask:0xf bound_ctrl:1
	v_fmamk_f32 v73, v73, 0x3baaaaab, v228
	v_cmp_gt_f32_e64 s[0:1], s95, v73
	v_mul_f32_e32 v87, 0x4b800000, v73
	s_nop 0
	v_cndmask_b32_e64 v73, v73, v87, s[0:1]
	v_rsq_f32_e32 v73, v73
	s_nop 0
	v_mul_f32_e32 v87, 0x45800000, v73
	v_cndmask_b32_e64 v73, v73, v87, s[0:1]
	v_mul_f32_e32 v106, 0x3dd53b94, v73
	v_pk_mul_f32 v[78:79], v[78:79], v[106:107] op_sel_hi:[1,0]
	v_pk_mul_f32 v[108:109], v[110:111], v[106:107] op_sel_hi:[1,0]
	v_pk_mul_f32 v[80:81], v[80:81], v[106:107] op_sel_hi:[1,0]
	v_pk_mul_f32 v[104:105], v[104:105], v[106:107] op_sel_hi:[1,0]
	v_pk_mul_f32 v[78:79], v[46:47], v[78:79]
	v_pk_mul_f32 v[108:109], v[48:49], v[108:109]
	v_pk_mul_f32 v[80:81], v[42:43], v[80:81]
	v_pk_mul_f32 v[104:105], v[44:45], v[104:105]
	v_cvt_pk_bf16_f32 v78, v78, v79
	v_cvt_pk_bf16_f32 v79, v108, v109
	v_cvt_pk_bf16_f32 v80, v80, v81
	v_cvt_pk_bf16_f32 v81, v104, v105
	flat_store_dwordx4 v[76:77], v[78:81]
	v_lshlrev_b32_e32 v110, 16, v82
	v_and_b32_e32 v111, 0xffff0000, v82
	v_pk_mul_f32 v[80:81], v[102:103], v[106:107] op_sel_hi:[1,0]
	v_pk_mul_f32 v[78:79], v[90:91], v[106:107] op_sel_hi:[1,0]
	v_pk_mul_f32 v[80:81], v[64:65], v[80:81]
	v_pk_mul_f32 v[78:79], v[66:67], v[78:79]
	v_pk_mul_f32 v[90:91], v[54:55], v[80:81]
	v_pk_mul_f32 v[80:81], v[52:53], v[80:81]
	v_pk_fma_f32 v[90:91], v[52:53], v[78:79], v[90:91] neg_lo:[0,0,1] neg_hi:[0,0,1]
	v_pk_fma_f32 v[78:79], v[54:55], v[78:79], v[80:81]
	v_cvt_pk_bf16_f32 v73, v90, v91
	flat_store_dword v[68:69], v73 offset:256
	v_cvt_pk_bf16_f32 v73, v78, v79
	v_lshlrev_b32_e32 v78, 16, v93
	v_and_b32_e32 v79, 0xffff0000, v93
	v_lshlrev_b32_e32 v80, 16, v120
	v_and_b32_e32 v81, 0xffff0000, v120
	v_pk_mul_f32 v[112:113], v[86:87], v[78:79] op_sel_hi:[0,1]
	v_pk_mul_f32 v[114:115], v[86:87], v[80:81] op_sel_hi:[0,1]
	v_pk_mul_f32 v[78:79], v[112:113], v[112:113]
	v_pk_mul_f32 v[80:81], v[114:115], v[114:115]
	flat_store_dword v[68:69], v73 offset:320
	v_lshlrev_b32_e32 v106, 16, v83
	v_and_b32_e32 v107, 0xffff0000, v83
	v_pk_mul_f32 v[82:83], v[86:87], v[110:111] op_sel_hi:[0,1]
	v_add_f32_e32 v73, v80, v81
	v_add_f32_e32 v78, v78, v79
	v_pk_mul_f32 v[110:111], v[82:83], v[82:83]
	v_add_f32_e32 v73, v78, v73
	v_pk_mul_f32 v[106:107], v[86:87], v[106:107] op_sel_hi:[0,1]
	v_add_f32_e32 v73, v110, v73
	v_lshlrev_b32_e32 v104, 16, v84
	v_and_b32_e32 v105, 0xffff0000, v84
	v_pk_mul_f32 v[108:109], v[106:107], v[106:107]
	v_add_f32_e32 v73, v111, v73
	v_lshlrev_b32_e32 v90, 16, v85
	v_and_b32_e32 v91, 0xffff0000, v85
	v_pk_mul_f32 v[84:85], v[86:87], v[104:105] op_sel_hi:[0,1]
	v_add_f32_e32 v73, v108, v73
	v_pk_mul_f32 v[104:105], v[84:85], v[84:85]
	v_add_f32_e32 v73, v109, v73
	v_pk_mul_f32 v[90:91], v[86:87], v[90:91] op_sel_hi:[0,1]
	v_add_f32_e32 v73, v104, v73
	v_pk_mul_f32 v[102:103], v[90:91], v[90:91]
	v_add_f32_e32 v73, v105, v73
	v_add_f32_e32 v73, v102, v73
	v_add_f32_e32 v73, v103, v73
	s_nop 1
	v_add_f32_dpp v73, v73, v73 row_ror:1 row_mask:0xf bank_mask:0xf bound_ctrl:1
	s_nop 1
	v_add_f32_dpp v73, v73, v73 row_ror:2 row_mask:0xf bank_mask:0xf bound_ctrl:1
	s_nop 1
	v_add_f32_dpp v73, v73, v73 row_ror:4 row_mask:0xf bank_mask:0xf bound_ctrl:1
	s_nop 1
	v_add_f32_dpp v73, v73, v73 row_ror:8 row_mask:0xf bank_mask:0xf bound_ctrl:1
	v_fmamk_f32 v73, v73, 0x3baaaaab, v228
	v_cmp_gt_f32_e64 s[0:1], s95, v73
	v_mul_f32_e32 v78, 0x4b800000, v73
	s_nop 0
	v_cndmask_b32_e64 v73, v73, v78, s[0:1]
	v_rsq_f32_e32 v73, v73
	s_nop 0
	v_mul_f32_e32 v78, 0x45800000, v73
	v_cndmask_b32_e64 v73, v73, v78, s[0:1]
	v_mul_f32_e32 v102, 0x3dd53b94, v73
	v_pk_mul_f32 v[78:79], v[82:83], v[102:103] op_sel_hi:[1,0]
	v_pk_mul_f32 v[80:81], v[106:107], v[102:103] op_sel_hi:[1,0]
	v_pk_mul_f32 v[78:79], v[46:47], v[78:79]
	v_pk_mul_f32 v[80:81], v[48:49], v[80:81]
	v_cvt_pk_bf16_f32 v78, v78, v79
	v_cvt_pk_bf16_f32 v79, v80, v81
	v_pk_mul_f32 v[80:81], v[84:85], v[102:103] op_sel_hi:[1,0]
; DI unsigned pk2(float lo, float hi) { f32x2 v = {lo, hi}; return __builtin_bit_cast(unsigned, __builtin_convertvector(v, bf2_t)); }
; DI float bflo(unsigned w) { return __uint_as_float(w << 16); }
; DI float bfhi(unsigned w) { return __uint_as_float(w & 0xffff0000u); }
; DI float red16(float v, int lane) { (void)lane; v += DPP_ROR(v, 1); v += DPP_ROR(v, 2); v += DPP_ROR(v, 4); v += DPP_ROR(v, 8); return v; }
; DI void unpack8(const u32x4 w, float (&v)[8]) { v[0] = bflo(w.x); v[1] = bfhi(w.x); v[2] = bflo(w.y); v[3] = bfhi(w.y); v[4] = bflo(w.z); v[5] = bfhi(w.z); v[6] = bflo(w.w); v[7] = bfhi(w.w); }
; DI void finalize_tile(const Params& p, int l, int tile, LAS unsigned char* lds, int tid, int lane, int wave, const bool doq = true) {
;     ...
;         if (doq)
; #pragma unroll
;         for (int h = 0; h < 4; ++h) {
;             bf16_t* qp = QR + t * 768 + h * 192;
;             const u32x4 qa = qa4[h]; const unsigned r1 = r14[h], r2 = r24[h];
;             unpack8(qa, v);
;             const float y1a = bflo(r1) * rcq, y1b = bfhi(r1) * rcq, y2a = bflo(r2) * rcq, y2b = bfhi(r2) * rcq;
;             float ss = (y1a * y1a + y1b * y1b) + (y2a * y2a + y2b * y2b);
; #pragma unroll
;             for (int e = 0; e < 8; ++e) { v[e] *= rcq; ss += v[e] * v[e]; }
;             ss = red16(ss, lane);
;             const float rq = rsqrtf(ss * (1.0f / 192.0f) + EPS) * QSCALE;
;             const f32x4 g0 = qg0, g1 = qg1; const f32x2 gr1 = qgr1, gr2 = qgr2;
;             u32x4 o; o.x = pk2(v[0] * rq * g0.x, v[1] * rq * g0.y); o.y = pk2(v[2] * rq * g0.z, v[3] * rq * g0.w); o.z = pk2(v[4] * rq * g1.x, v[5] * rq * g1.y); o.w = pk2(v[6] * rq * g1.z, v[7] * rq * g1.w);
;             *(u32x4*)(qp + 8 * i) = o;
;             const float a1 = y1a * rq * gr1.x, b1 = y1b * rq * gr1.y, a2 = y2a * rq * gr2.x, b2 = y2b * rq * gr2.y;
;             *(unsigned*)(qp + 128 + 2 * i) = pk2(a1 * cs.x - a2 * sn.x, b1 * cs.y - b2 * sn.y);
;             *(unsigned*)(qp + 160 + 2 * i) = pk2(a1 * sn.x + a2 * cs.x, b1 * sn.y + b2 * cs.y);
;         }
	v_pk_mul_f32 v[82:83], v[90:91], v[102:103] op_sel_hi:[1,0]
	v_pk_mul_f32 v[80:81], v[42:43], v[80:81]
	v_pk_mul_f32 v[82:83], v[44:45], v[82:83]
	v_cvt_pk_bf16_f32 v80, v80, v81
	v_cvt_pk_bf16_f32 v81, v82, v83
	flat_store_dwordx4 v[76:77], v[78:81] offset:384
	v_lshlrev_b32_e32 v106, 16, v94
	v_and_b32_e32 v107, 0xffff0000, v94
	v_pk_mul_f32 v[80:81], v[114:115], v[102:103] op_sel_hi:[1,0]
	v_pk_mul_f32 v[78:79], v[112:113], v[102:103] op_sel_hi:[1,0]
	v_pk_mul_f32 v[80:81], v[64:65], v[80:81]
	v_pk_mul_f32 v[78:79], v[66:67], v[78:79]
	v_pk_mul_f32 v[82:83], v[54:55], v[80:81]
	v_pk_mul_f32 v[80:81], v[52:53], v[80:81]
	v_pk_fma_f32 v[82:83], v[52:53], v[78:79], v[82:83] neg_lo:[0,0,1] neg_hi:[0,0,1]
	v_pk_fma_f32 v[78:79], v[54:55], v[78:79], v[80:81]
	v_cvt_pk_bf16_f32 v73, v82, v83
	flat_store_dword v[68:69], v73 offset:640
	v_cvt_pk_bf16_f32 v73, v78, v79
	v_lshlrev_b32_e32 v78, 16, v121
	v_and_b32_e32 v79, 0xffff0000, v121
	v_lshlrev_b32_e32 v80, 16, v122
	v_and_b32_e32 v81, 0xffff0000, v122
	v_pk_mul_f32 v[108:109], v[86:87], v[78:79] op_sel_hi:[0,1]
	v_pk_mul_f32 v[110:111], v[86:87], v[80:81] op_sel_hi:[0,1]
	v_pk_mul_f32 v[78:79], v[108:109], v[108:109]
	v_pk_mul_f32 v[80:81], v[110:111], v[110:111]
	flat_store_dword v[68:69], v73 offset:704
	v_lshlrev_b32_e32 v102, 16, v95
	v_and_b32_e32 v103, 0xffff0000, v95
	v_pk_mul_f32 v[94:95], v[86:87], v[106:107] op_sel_hi:[0,1]
	v_add_f32_e32 v73, v80, v81
	v_add_f32_e32 v78, v78, v79
	v_pk_mul_f32 v[106:107], v[94:95], v[94:95]
	v_add_f32_e32 v73, v78, v73
	v_pk_mul_f32 v[102:103], v[86:87], v[102:103] op_sel_hi:[0,1]
	v_add_f32_e32 v73, v106, v73
	v_lshlrev_b32_e32 v90, 16, v96
	v_and_b32_e32 v91, 0xffff0000, v96
	v_pk_mul_f32 v[104:105], v[102:103], v[102:103]
	v_add_f32_e32 v73, v107, v73
	v_pk_mul_f32 v[90:91], v[86:87], v[90:91] op_sel_hi:[0,1]
	v_add_f32_e32 v73, v104, v73
	v_lshlrev_b32_e32 v82, 16, v97
	v_and_b32_e32 v83, 0xffff0000, v97
	v_pk_mul_f32 v[96:97], v[90:91], v[90:91]
	v_add_f32_e32 v73, v105, v73
	v_pk_mul_f32 v[82:83], v[86:87], v[82:83] op_sel_hi:[0,1]
	v_add_f32_e32 v73, v96, v73
	v_pk_mul_f32 v[84:85], v[82:83], v[82:83]
	v_add_f32_e32 v73, v97, v73
	v_add_f32_e32 v73, v84, v73
	v_add_f32_e32 v73, v85, v73
	v_lshlrev_b32_e32 v96, 16, v99
	v_and_b32_e32 v97, 0xffff0000, v99
	v_add_f32_dpp v73, v73, v73 row_ror:1 row_mask:0xf bank_mask:0xf bound_ctrl:1
	v_pk_mul_f32 v[96:97], v[86:87], v[96:97] op_sel_hi:[0,1]
	s_nop 0
	v_add_f32_dpp v73, v73, v73 row_ror:2 row_mask:0xf bank_mask:0xf bound_ctrl:1
	s_nop 1
	v_add_f32_dpp v73, v73, v73 row_ror:4 row_mask:0xf bank_mask:0xf bound_ctrl:1
	s_nop 1
	v_add_f32_dpp v73, v73, v73 row_ror:8 row_mask:0xf bank_mask:0xf bound_ctrl:1
	v_fmamk_f32 v73, v73, 0x3baaaaab, v228
	v_cmp_gt_f32_e64 s[0:1], s95, v73
	v_mul_f32_e32 v78, 0x4b800000, v73
	s_nop 0
	v_cndmask_b32_e64 v73, v73, v78, s[0:1]
	v_rsq_f32_e32 v73, v73
	s_nop 0
	v_mul_f32_e32 v78, 0x45800000, v73
	v_cndmask_b32_e64 v73, v73, v78, s[0:1]
	v_mul_f32_e32 v84, 0x3dd53b94, v73
	v_pk_mul_f32 v[78:79], v[94:95], v[84:85] op_sel_hi:[1,0]
	v_pk_mul_f32 v[80:81], v[102:103], v[84:85] op_sel_hi:[1,0]
	v_pk_mul_f32 v[78:79], v[46:47], v[78:79]
	v_pk_mul_f32 v[80:81], v[48:49], v[80:81]
	v_cvt_pk_bf16_f32 v78, v78, v79
	v_cvt_pk_bf16_f32 v79, v80, v81
	v_pk_mul_f32 v[80:81], v[90:91], v[84:85] op_sel_hi:[1,0]
	v_pk_mul_f32 v[82:83], v[82:83], v[84:85] op_sel_hi:[1,0]
	v_pk_mul_f32 v[80:81], v[42:43], v[80:81]
	v_pk_mul_f32 v[82:83], v[44:45], v[82:83]
	v_cvt_pk_bf16_f32 v80, v80, v81
	v_cvt_pk_bf16_f32 v81, v82, v83
	flat_store_dwordx4 v[76:77], v[78:81] offset:768
	v_lshlrev_b32_e32 v90, 16, v100
	v_and_b32_e32 v91, 0xffff0000, v100
	v_pk_mul_f32 v[80:81], v[110:111], v[84:85] op_sel_hi:[1,0]
	v_pk_mul_f32 v[78:79], v[108:109], v[84:85] op_sel_hi:[1,0]
	v_pk_mul_f32 v[80:81], v[64:65], v[80:81]
	v_pk_mul_f32 v[78:79], v[66:67], v[78:79]
	v_pk_mul_f32 v[82:83], v[54:55], v[80:81]
	v_pk_mul_f32 v[80:81], v[52:53], v[80:81]
	v_pk_fma_f32 v[82:83], v[52:53], v[78:79], v[82:83] neg_lo:[0,0,1] neg_hi:[0,0,1]
	v_pk_fma_f32 v[78:79], v[54:55], v[78:79], v[80:81]
	v_cvt_pk_bf16_f32 v73, v82, v83
	flat_store_dword v[68:69], v73 offset:1024
	v_cvt_pk_bf16_f32 v73, v78, v79
	v_lshlrev_b32_e32 v78, 16, v123
	v_and_b32_e32 v79, 0xffff0000, v123
	v_lshlrev_b32_e32 v80, 16, v124
	v_and_b32_e32 v81, 0xffff0000, v124
	v_lshlrev_b32_e32 v82, 16, v101
	v_and_b32_e32 v83, 0xffff0000, v101
	v_lshlrev_b32_e32 v102, 16, v98
	v_and_b32_e32 v103, 0xffff0000, v98
	v_pk_mul_f32 v[78:79], v[86:87], v[78:79] op_sel_hi:[0,1]
	v_pk_mul_f32 v[80:81], v[86:87], v[80:81] op_sel_hi:[0,1]
	v_pk_mul_f32 v[82:83], v[86:87], v[82:83] op_sel_hi:[0,1]
	v_pk_mul_f32 v[90:91], v[86:87], v[90:91] op_sel_hi:[0,1]
	v_pk_mul_f32 v[98:99], v[86:87], v[102:103] op_sel_hi:[0,1]
	v_pk_mul_f32 v[86:87], v[78:79], v[78:79]
	v_pk_mul_f32 v[104:105], v[80:81], v[80:81]
	flat_store_dword v[68:69], v73 offset:1088
	v_add_f32_e32 v73, v104, v105
	v_add_f32_e32 v86, v86, v87
	v_pk_mul_f32 v[102:103], v[98:99], v[98:99]
	v_add_f32_e32 v73, v86, v73
	v_add_f32_e32 v73, v102, v73
	v_pk_mul_f32 v[100:101], v[96:97], v[96:97]
	v_add_f32_e32 v73, v103, v73
	v_add_f32_e32 v73, v100, v73
	v_pk_mul_f32 v[94:95], v[90:91], v[90:91]
	v_add_f32_e32 v73, v101, v73
	v_add_f32_e32 v73, v94, v73
	v_pk_mul_f32 v[84:85], v[82:83], v[82:83]
	v_add_f32_e32 v73, v95, v73
	v_add_f32_e32 v73, v84, v73
	v_add_f32_e32 v73, v85, v73
	s_nop 1
	v_add_f32_dpp v73, v73, v73 row_ror:1 row_mask:0xf bank_mask:0xf bound_ctrl:1
	s_nop 1
	v_add_f32_dpp v73, v73, v73 row_ror:2 row_mask:0xf bank_mask:0xf bound_ctrl:1
	s_nop 1
	v_add_f32_dpp v73, v73, v73 row_ror:4 row_mask:0xf bank_mask:0xf bound_ctrl:1
; #define LAS __attribute__((address_space(3)))
; DI unsigned pk2(float lo, float hi) { f32x2 v = {lo, hi}; return __builtin_bit_cast(unsigned, __builtin_convertvector(v, bf2_t)); }
; DI float red16(float v, int lane) { (void)lane; v += DPP_ROR(v, 1); v += DPP_ROR(v, 2); v += DPP_ROR(v, 4); v += DPP_ROR(v, 8); return v; }
; DI void finalize_tile(const Params& p, int l, int tile, LAS unsigned char* lds, int tid, int lane, int wave, const bool doq = true) {
;     ...
;             u32x4 o; o.x = pk2(v[0] * rq * g0.x, v[1] * rq * g0.y); o.y = pk2(v[2] * rq * g0.z, v[3] * rq * g0.w); o.z = pk2(v[4] * rq * g1.x, v[5] * rq * g1.y); o.w = pk2(v[6] * rq * g1.z, v[7] * rq * g1.w);
;             *(u32x4*)(qp + 8 * i) = o;
;             const float a1 = y1a * rq * gr1.x, b1 = y1b * rq * gr1.y, a2 = y2a * rq * gr2.x, b2 = y2b * rq * gr2.y;
;             *(unsigned*)(qp + 128 + 2 * i) = pk2(a1 * cs.x - a2 * sn.x, b1 * cs.y - b2 * sn.y);
;             *(unsigned*)(qp + 160 + 2 * i) = pk2(a1 * sn.x + a2 * cs.x, b1 * sn.y + b2 * cs.y);
;         }
; #pragma unroll
;         for (int h = 0; h < 4; ++h) {
;             const u32x4 ka = ka4[h], va = va4[h];
;             unpack8(ka, v);
;             float ss = 0.f;
; #pragma unroll
;             for (int e = 0; e < 8; ++e) { v[e] *= rckv; ss += v[e] * v[e]; }
;             ss = red16(ss, lane) + s3;
;             const float rk = rsqrtf(ss * (1.0f / 192.0f) + EPS);
;             const f32x4 g0 = kg0, g1 = kg1; const f32x2 gr1 = kgr1, gr2 = kgr2;
;             bf16_t* ko = KB + t * 768 + h * 192;
;             u32x4 o; o.x = pk2(v[0] * rk * g0.x, v[1] * rk * g0.y); o.y = pk2(v[2] * rk * g0.z, v[3] * rk * g0.w); o.z = pk2(v[4] * rk * g1.x, v[5] * rk * g1.y); o.w = pk2(v[6] * rk * g1.z, v[7] * rk * g1.w);
;             *(u32x4*)(ko + 8 * i) = o;
;             const float a1 = x1a * rk * gr1.x, b1 = x1b * rk * gr1.y, a2 = x2a * rk * gr2.x, b2 = x2b * rk * gr2.y;
;             *(unsigned*)(ko + 128 + 2 * i) = pk2(a1 * cs.x - a2 * sn.x, b1 * cs.y - b2 * sn.y);
;             *(unsigned*)(ko + 160 + 2 * i) = pk2(a1 * sn.x + a2 * cs.x, b1 * sn.y + b2 * cs.y);
;             unpack8(va, w);
;             u32x4 vo; vo.x = pk2(w[0] * rckv, w[1] * rckv); vo.y = pk2(w[2] * rckv, w[3] * rckv); vo.z = pk2(w[4] * rckv, w[5] * rckv); vo.w = pk2(w[6] * rckv, w[7] * rckv);
;             *(LAS u32x4*)(VL + tl * 512 + h * 128 + 8 * i) = vo;
;         }
	s_nop 1
	v_add_f32_dpp v73, v73, v73 row_ror:8 row_mask:0xf bank_mask:0xf bound_ctrl:1
	v_fmamk_f32 v73, v73, 0x3baaaaab, v228
	v_cmp_gt_f32_e64 s[0:1], s95, v73
	v_mul_f32_e32 v84, 0x4b800000, v73
	s_nop 0
	v_cndmask_b32_e64 v73, v73, v84, s[0:1]
	v_rsq_f32_e32 v73, v73
	s_nop 0
	v_mul_f32_e32 v84, 0x45800000, v73
	v_cndmask_b32_e64 v73, v73, v84, s[0:1]
	v_mul_f32_e32 v84, 0x3dd53b94, v73
	v_pk_mul_f32 v[86:87], v[98:99], v[84:85] op_sel_hi:[1,0]
	s_nop 0
	v_pk_mul_f32 v[46:47], v[46:47], v[86:87]
	v_pk_mul_f32 v[86:87], v[96:97], v[84:85] op_sel_hi:[1,0]
	v_cvt_pk_bf16_f32 v46, v46, v47
	v_pk_mul_f32 v[48:49], v[48:49], v[86:87]
	s_nop 0
	v_cvt_pk_bf16_f32 v47, v48, v49
	v_pk_mul_f32 v[48:49], v[90:91], v[84:85] op_sel_hi:[1,0]
	s_nop 0
	v_pk_mul_f32 v[42:43], v[42:43], v[48:49]
	s_nop 0
	v_cvt_pk_bf16_f32 v48, v42, v43
	v_pk_mul_f32 v[42:43], v[82:83], v[84:85] op_sel_hi:[1,0]
	s_nop 0
	v_pk_mul_f32 v[42:43], v[44:45], v[42:43]
	v_pk_mul_f32 v[44:45], v[80:81], v[84:85] op_sel_hi:[1,0]
	v_cvt_pk_bf16_f32 v49, v42, v43
	v_pk_mul_f32 v[42:43], v[78:79], v[84:85] op_sel_hi:[1,0]
	v_pk_mul_f32 v[44:45], v[64:65], v[44:45]
	flat_store_dwordx4 v[76:77], v[46:49] offset:1152
	v_pk_mul_f32 v[42:43], v[66:67], v[42:43]
	v_lshlrev_b32_e32 v64, 16, v38
	v_pk_mul_f32 v[46:47], v[54:55], v[44:45]
	v_pk_mul_f32 v[44:45], v[52:53], v[44:45]
	v_pk_fma_f32 v[46:47], v[52:53], v[42:43], v[46:47] neg_lo:[0,0,1] neg_hi:[0,0,1]
	v_pk_fma_f32 v[42:43], v[54:55], v[42:43], v[44:45]
	v_cvt_pk_bf16_f32 v46, v46, v47
	v_cvt_pk_bf16_f32 v42, v42, v43
	flat_store_dword v[68:69], v42 offset:1472
	v_cndmask_b32_e32 v42, v75, v89, vcc
	v_lshlrev_b32_e32 v48, 16, v40
	v_and_b32_e32 v49, 0xffff0000, v40
	v_and_b32_e32 v65, 0xffff0000, v38
	flat_store_dword v[68:69], v46 offset:1408
	v_lshlrev_b32_e32 v46, 16, v41
	v_and_b32_e32 v47, 0xffff0000, v41
	v_pk_mul_f32 v[40:41], v[42:43], v[48:49] op_sel_hi:[0,1]
	v_lshlrev_b32_e32 v48, 16, v39
	v_and_b32_e32 v49, 0xffff0000, v39
	v_pk_mul_f32 v[64:65], v[42:43], v[64:65] op_sel_hi:[0,1]
	v_pk_mul_f32 v[48:49], v[42:43], v[48:49] op_sel_hi:[0,1]
	v_pk_mul_f32 v[38:39], v[64:65], v[64:65]
	v_pk_mul_f32 v[68:69], v[48:49], v[48:49]
	v_add_f32_e32 v38, v38, v39
	v_add_f32_e32 v38, v68, v38
	v_pk_mul_f32 v[46:47], v[42:43], v[46:47] op_sel_hi:[0,1]
	v_add_f32_e32 v38, v69, v38
	v_pk_mul_f32 v[66:67], v[46:47], v[46:47]
	v_fmac_f32_e32 v38, v40, v40
	v_pk_fma_f32 v[68:69], v[40:41], v[40:41], v[38:39] op_sel_hi:[1,1,0]
	v_mov_b32_e32 v75, v67
	v_pk_mul_f32 v[66:67], v[56:57], v[56:57]
	v_mad_i64_i32 v[44:45], s[0:1], v72, s76, v[70:71]
	v_mov_b32_e32 v70, v56
	v_mov_b32_e32 v71, v46
	v_mov_b32_e32 v68, v67
	v_pk_fma_f32 v[66:67], v[70:71], v[70:71], v[68:69]
	v_mov_b32_e32 v68, v1
	v_pk_add_f32 v[66:67], v[66:67], v[74:75]
	v_mov_b32_e32 v69, v1
	v_lshl_add_u64 v[38:39], v[44:45], 0, v[0:1]
	v_mov_b32_dpp v68, v66 row_ror:1 row_mask:0xf bank_mask:0xf
	v_mov_b32_dpp v69, v67 row_ror:1 row_mask:0xf bank_mask:0xf
	v_pk_add_f32 v[66:67], v[66:67], v[68:69]
	v_mov_b32_e32 v68, v1
	v_mov_b32_e32 v69, v1
	v_lshl_add_u64 v[44:45], v[44:45], 0, v[50:51]
	v_mov_b32_dpp v68, v66 row_ror:2 row_mask:0xf bank_mask:0xf
	v_mov_b32_dpp v69, v67 row_ror:2 row_mask:0xf bank_mask:0xf
	v_pk_add_f32 v[66:67], v[66:67], v[68:69]
	v_mov_b32_e32 v68, v1
	v_mov_b32_e32 v69, v1
	v_lshlrev_b32_e32 v50, 16, v30
	v_mov_b32_dpp v68, v66 row_ror:4 row_mask:0xf bank_mask:0xf
	v_mov_b32_dpp v69, v67 row_ror:4 row_mask:0xf bank_mask:0xf
	v_pk_add_f32 v[66:67], v[66:67], v[68:69]
	v_mov_b32_e32 v68, v1
	v_mov_b32_e32 v69, v1
	v_and_b32_e32 v51, 0xffff0000, v30
	v_mov_b32_dpp v68, v66 row_ror:8 row_mask:0xf bank_mask:0xf
	v_mov_b32_dpp v69, v67 row_ror:8 row_mask:0xf bank_mask:0xf
	v_pk_add_f32 v[68:69], v[66:67], v[68:69]
	s_and_b32 s1, s18, 0xfffffe00
	v_add_f32_e32 v0, v68, v69
	v_fmamk_f32 v0, v0, 0x3baaaaab, v228
	v_cmp_gt_f32_e32 vcc, s95, v0
	v_mul_f32_e32 v43, 0x4b800000, v0
	s_and_b32 s0, s19, 0xfc0
	v_cndmask_b32_e32 v0, v0, v43, vcc
	v_rsq_f32_e32 v0, v0
	s_lshl_b32 s92, s0, 1
	s_add_i32 s19, s19, s37
	s_add_i32 s18, s18, s97
	v_mul_f32_e32 v43, 0x45800000, v0
	v_cndmask_b32_e32 v0, v0, v43, vcc
	v_pk_mul_f32 v[40:41], v[40:41], v[0:1] op_sel_hi:[1,0]
	v_pk_mul_f32 v[64:65], v[64:65], v[0:1] op_sel_hi:[1,0]
	v_pk_mul_f32 v[40:41], v[6:7], v[40:41]
	v_pk_mul_f32 v[48:49], v[48:49], v[0:1] op_sel_hi:[1,0]
	v_cvt_pk_bf16_f32 v66, v40, v41
	v_pk_mul_f32 v[40:41], v[46:47], v[0:1] op_sel_hi:[1,0]
	v_pk_mul_f32 v[46:47], v[0:1], v[58:59] op_sel_hi:[0,1]
	v_pk_mul_f32 v[40:41], v[8:9], v[40:41]
	v_pk_mul_f32 v[64:65], v[10:11], v[64:65]
	v_pk_mul_f32 v[48:49], v[12:13], v[48:49]
	v_cvt_pk_bf16_f32 v67, v40, v41
	v_pk_mul_f32 v[40:41], v[0:1], v[56:57] op_sel_hi:[0,1]
	v_pk_mul_f32 v[46:47], v[60:61], v[46:47]
	v_cvt_pk_bf16_f32 v64, v64, v65
	v_cvt_pk_bf16_f32 v65, v48, v49
	v_pk_mul_f32 v[40:41], v[62:63], v[40:41]
	v_pk_mul_f32 v[48:49], v[54:55], v[46:47]
	v_pk_mul_f32 v[46:47], v[52:53], v[46:47]
	v_pk_fma_f32 v[48:49], v[52:53], v[40:41], v[48:49] neg_lo:[0,0,1] neg_hi:[0,0,1]
	v_pk_fma_f32 v[40:41], v[54:55], v[40:41], v[46:47]
	v_cvt_pk_bf16_f32 v0, v48, v49
	flat_store_dword v[44:45], v0 offset:256
	v_cvt_pk_bf16_f32 v0, v40, v41
	v_lshlrev_b32_e32 v40, 16, v34
	v_and_b32_e32 v41, 0xffff0000, v34
	v_pk_mul_f32 v[40:41], v[42:43], v[40:41] op_sel_hi:[0,1]
	v_cvt_pk_bf16_f32 v34, v40, v41
	v_lshlrev_b32_e32 v40, 16, v35
	v_and_b32_e32 v41, 0xffff0000, v35
	v_pk_mul_f32 v[40:41], v[42:43], v[40:41] op_sel_hi:[0,1]
	v_cvt_pk_bf16_f32 v35, v40, v41
	v_lshlrev_b32_e32 v40, 16, v36
	v_and_b32_e32 v41, 0xffff0000, v36
	v_pk_mul_f32 v[40:41], v[42:43], v[40:41] op_sel_hi:[0,1]
; #define LAS __attribute__((address_space(3)))
; DI unsigned pk2(float lo, float hi) { f32x2 v = {lo, hi}; return __builtin_bit_cast(unsigned, __builtin_convertvector(v, bf2_t)); }
; DI float red16(float v, int lane) { (void)lane; v += DPP_ROR(v, 1); v += DPP_ROR(v, 2); v += DPP_ROR(v, 4); v += DPP_ROR(v, 8); return v; }
; DI void unpack8(const u32x4 w, float (&v)[8]) { v[0] = bflo(w.x); v[1] = bfhi(w.x); v[2] = bflo(w.y); v[3] = bfhi(w.y); v[4] = bflo(w.z); v[5] = bfhi(w.z); v[6] = bflo(w.w); v[7] = bfhi(w.w); }
; DI void finalize_tile(const Params& p, int l, int tile, LAS unsigned char* lds, int tid, int lane, int wave, const bool doq = true) {
;     ...
; #pragma unroll
;         for (int h = 0; h < 4; ++h) {
;             const u32x4 ka = ka4[h], va = va4[h];
;             unpack8(ka, v);
;             float ss = 0.f;
; #pragma unroll
;             for (int e = 0; e < 8; ++e) { v[e] *= rckv; ss += v[e] * v[e]; }
;             ss = red16(ss, lane) + s3;
;             const float rk = rsqrtf(ss * (1.0f / 192.0f) + EPS);
;             const f32x4 g0 = kg0, g1 = kg1; const f32x2 gr1 = kgr1, gr2 = kgr2;
;             bf16_t* ko = KB + t * 768 + h * 192;
;             u32x4 o; o.x = pk2(v[0] * rk * g0.x, v[1] * rk * g0.y); o.y = pk2(v[2] * rk * g0.z, v[3] * rk * g0.w); o.z = pk2(v[4] * rk * g1.x, v[5] * rk * g1.y); o.w = pk2(v[6] * rk * g1.z, v[7] * rk * g1.w);
;             *(u32x4*)(ko + 8 * i) = o;
;             const float a1 = x1a * rk * gr1.x, b1 = x1b * rk * gr1.y, a2 = x2a * rk * gr2.x, b2 = x2b * rk * gr2.y;
;             *(unsigned*)(ko + 128 + 2 * i) = pk2(a1 * cs.x - a2 * sn.x, b1 * cs.y - b2 * sn.y);
;             *(unsigned*)(ko + 160 + 2 * i) = pk2(a1 * sn.x + a2 * cs.x, b1 * sn.y + b2 * cs.y);
;             unpack8(va, w);
;             u32x4 vo; vo.x = pk2(w[0] * rckv, w[1] * rckv); vo.y = pk2(w[2] * rckv, w[3] * rckv); vo.z = pk2(w[4] * rckv, w[5] * rckv); vo.w = pk2(w[6] * rckv, w[7] * rckv);
;             *(LAS u32x4*)(VL + tl * 512 + h * 128 + 8 * i) = vo;
;         }
	v_cvt_pk_bf16_f32 v36, v40, v41
	v_lshlrev_b32_e32 v40, 16, v37
	v_and_b32_e32 v41, 0xffff0000, v37
	v_lshlrev_b32_e32 v46, 16, v31
	v_and_b32_e32 v47, 0xffff0000, v31
	v_pk_mul_f32 v[30:31], v[42:43], v[50:51] op_sel_hi:[0,1]
	v_pk_mul_f32 v[40:41], v[42:43], v[40:41] op_sel_hi:[0,1]
	v_pk_mul_f32 v[46:47], v[42:43], v[46:47] op_sel_hi:[0,1]
	v_pk_mul_f32 v[50:51], v[30:31], v[30:31]
	flat_store_dword v[44:45], v0 offset:320
	v_cvt_pk_bf16_f32 v37, v40, v41
	v_lshlrev_b32_e32 v40, 16, v32
	v_and_b32_e32 v41, 0xffff0000, v32
	v_pk_mul_f32 v[48:49], v[46:47], v[46:47]
	v_add_f32_e32 v0, v50, v51
	flat_store_dwordx4 v[38:39], v[64:67]
	ds_write_b128 v88, v[34:37] offset:4096
	v_lshlrev_b32_e32 v34, 16, v33
	v_and_b32_e32 v35, 0xffff0000, v33
	v_pk_mul_f32 v[32:33], v[42:43], v[40:41] op_sel_hi:[0,1]
	v_add_f32_e32 v0, v48, v0
	v_pk_mul_f32 v[40:41], v[32:33], v[32:33]
	v_add_f32_e32 v0, v49, v0
	v_pk_mul_f32 v[34:35], v[42:43], v[34:35] op_sel_hi:[0,1]
	v_add_f32_e32 v0, v40, v0
	v_pk_mul_f32 v[36:37], v[34:35], v[34:35]
	v_add_f32_e32 v0, v41, v0
	v_add_f32_e32 v0, v36, v0
	v_add_f32_e32 v0, v37, v0
	s_cmpk_gt_i32 s22, 0xff
	s_nop 0
	v_add_f32_dpp v0, v0, v0 row_ror:1 row_mask:0xf bank_mask:0xf bound_ctrl:1
	s_nop 1
	v_add_f32_dpp v0, v0, v0 row_ror:2 row_mask:0xf bank_mask:0xf bound_ctrl:1
	s_nop 1
	v_add_f32_dpp v0, v0, v0 row_ror:4 row_mask:0xf bank_mask:0xf bound_ctrl:1
	s_nop 1
	v_add_f32_dpp v0, v0, v0 row_ror:8 row_mask:0xf bank_mask:0xf bound_ctrl:1
	v_add_f32_e32 v0, v68, v0
	v_fmamk_f32 v0, v0, 0x3baaaaab, v228
	v_cmp_gt_f32_e32 vcc, s95, v0
	v_mul_f32_e32 v36, 0x4b800000, v0
	s_nop 0
	v_cndmask_b32_e32 v0, v0, v36, vcc
	v_rsq_f32_e32 v0, v0
	s_nop 0
	v_mul_f32_e32 v36, 0x45800000, v0
	v_cndmask_b32_e32 v0, v0, v36, vcc
	v_pk_mul_f32 v[30:31], v[30:31], v[0:1] op_sel_hi:[1,0]
	v_pk_mul_f32 v[36:37], v[46:47], v[0:1] op_sel_hi:[1,0]
	v_pk_mul_f32 v[32:33], v[32:33], v[0:1] op_sel_hi:[1,0]
	v_pk_mul_f32 v[34:35], v[34:35], v[0:1] op_sel_hi:[1,0]
	v_pk_mul_f32 v[30:31], v[10:11], v[30:31]
	v_pk_mul_f32 v[36:37], v[12:13], v[36:37]
	v_pk_mul_f32 v[32:33], v[6:7], v[32:33]
	v_pk_mul_f32 v[34:35], v[8:9], v[34:35]
	v_cvt_pk_bf16_f32 v30, v30, v31
	v_cvt_pk_bf16_f32 v31, v36, v37
	v_cvt_pk_bf16_f32 v32, v32, v33
	v_cvt_pk_bf16_f32 v33, v34, v35
	flat_store_dwordx4 v[38:39], v[30:33] offset:384
	v_lshlrev_b32_e32 v36, 16, v29
	v_and_b32_e32 v37, 0xffff0000, v29
	v_pk_mul_f32 v[32:33], v[0:1], v[58:59] op_sel_hi:[0,1]
	v_pk_mul_f32 v[30:31], v[0:1], v[56:57] op_sel_hi:[0,1]
	v_pk_mul_f32 v[32:33], v[60:61], v[32:33]
	v_pk_mul_f32 v[30:31], v[62:63], v[30:31]
	v_pk_mul_f32 v[34:35], v[54:55], v[32:33]
	v_pk_mul_f32 v[32:33], v[52:53], v[32:33]
	v_pk_fma_f32 v[34:35], v[52:53], v[30:31], v[34:35] neg_lo:[0,0,1] neg_hi:[0,0,1]
	v_pk_fma_f32 v[30:31], v[54:55], v[30:31], v[32:33]
	v_cvt_pk_bf16_f32 v0, v34, v35
	flat_store_dword v[44:45], v0 offset:640
	v_cvt_pk_bf16_f32 v0, v30, v31
	v_lshlrev_b32_e32 v30, 16, v26
	v_and_b32_e32 v31, 0xffff0000, v26
	v_lshlrev_b32_e32 v32, 16, v27
	v_and_b32_e32 v33, 0xffff0000, v27
	v_lshlrev_b32_e32 v34, 16, v28
	v_and_b32_e32 v35, 0xffff0000, v28
	v_pk_mul_f32 v[26:27], v[42:43], v[30:31] op_sel_hi:[0,1]
	v_pk_mul_f32 v[28:29], v[42:43], v[32:33] op_sel_hi:[0,1]
	v_cvt_pk_bf16_f32 v26, v26, v27
	v_cvt_pk_bf16_f32 v27, v28, v29
	v_pk_mul_f32 v[28:29], v[42:43], v[34:35] op_sel_hi:[0,1]
	v_pk_mul_f32 v[30:31], v[42:43], v[36:37] op_sel_hi:[0,1]
	v_cvt_pk_bf16_f32 v28, v28, v29
	v_cvt_pk_bf16_f32 v29, v30, v31
	v_lshlrev_b32_e32 v30, 16, v22
	v_and_b32_e32 v31, 0xffff0000, v22
	flat_store_dword v[44:45], v0 offset:704
	ds_write_b128 v88, v[26:29] offset:4352
	v_lshlrev_b32_e32 v26, 16, v23
	v_and_b32_e32 v27, 0xffff0000, v23
	v_pk_mul_f32 v[22:23], v[42:43], v[30:31] op_sel_hi:[0,1]
	v_pk_mul_f32 v[30:31], v[22:23], v[22:23]
	v_pk_mul_f32 v[26:27], v[42:43], v[26:27] op_sel_hi:[0,1]
	v_lshlrev_b32_e32 v28, 16, v24
	v_and_b32_e32 v29, 0xffff0000, v24
	v_pk_mul_f32 v[32:33], v[26:27], v[26:27]
	v_add_f32_e32 v0, v30, v31
	v_pk_mul_f32 v[28:29], v[42:43], v[28:29] op_sel_hi:[0,1]
	v_add_f32_e32 v0, v32, v0
	v_lshlrev_b32_e32 v24, 16, v25
	v_and_b32_e32 v25, 0xffff0000, v25
	v_pk_mul_f32 v[34:35], v[28:29], v[28:29]
	v_add_f32_e32 v0, v33, v0
	v_pk_mul_f32 v[36:37], v[42:43], v[24:25] op_sel_hi:[0,1]
	v_add_f32_e32 v0, v34, v0
	v_pk_mul_f32 v[24:25], v[36:37], v[36:37]
	v_add_f32_e32 v0, v35, v0
	v_add_f32_e32 v0, v24, v0
	v_add_f32_e32 v0, v25, v0
	s_nop 1
	v_add_f32_dpp v0, v0, v0 row_ror:1 row_mask:0xf bank_mask:0xf bound_ctrl:1
	s_nop 1
	v_add_f32_dpp v0, v0, v0 row_ror:2 row_mask:0xf bank_mask:0xf bound_ctrl:1
	s_nop 1
	v_add_f32_dpp v0, v0, v0 row_ror:4 row_mask:0xf bank_mask:0xf bound_ctrl:1
	s_nop 1
	v_add_f32_dpp v0, v0, v0 row_ror:8 row_mask:0xf bank_mask:0xf bound_ctrl:1
	v_add_f32_e32 v0, v68, v0
	v_fmamk_f32 v0, v0, 0x3baaaaab, v228
	v_cmp_gt_f32_e32 vcc, s95, v0
	v_mul_f32_e32 v24, 0x4b800000, v0
	s_nop 0
	v_cndmask_b32_e32 v0, v0, v24, vcc
	v_rsq_f32_e32 v0, v0
	s_nop 0
	v_mul_f32_e32 v24, 0x45800000, v0
	v_cndmask_b32_e32 v0, v0, v24, vcc
	v_pk_mul_f32 v[22:23], v[22:23], v[0:1] op_sel_hi:[1,0]
	v_pk_mul_f32 v[24:25], v[26:27], v[0:1] op_sel_hi:[1,0]
	v_pk_mul_f32 v[22:23], v[10:11], v[22:23]
	v_pk_mul_f32 v[24:25], v[12:13], v[24:25]
	v_cvt_pk_bf16_f32 v22, v22, v23
	v_cvt_pk_bf16_f32 v23, v24, v25
	v_pk_mul_f32 v[24:25], v[28:29], v[0:1] op_sel_hi:[1,0]
	v_pk_mul_f32 v[26:27], v[36:37], v[0:1] op_sel_hi:[1,0]
	v_pk_mul_f32 v[24:25], v[6:7], v[24:25]
	v_pk_mul_f32 v[26:27], v[8:9], v[26:27]
	v_cvt_pk_bf16_f32 v24, v24, v25
	v_cvt_pk_bf16_f32 v25, v26, v27
	flat_store_dwordx4 v[38:39], v[22:25] offset:768
; #define LAS __attribute__((address_space(3)))
; DI unsigned pk2(float lo, float hi) { f32x2 v = {lo, hi}; return __builtin_bit_cast(unsigned, __builtin_convertvector(v, bf2_t)); }
; DI float red16(float v, int lane) { (void)lane; v += DPP_ROR(v, 1); v += DPP_ROR(v, 2); v += DPP_ROR(v, 4); v += DPP_ROR(v, 8); return v; }
; DI void unpack8(const u32x4 w, float (&v)[8]) { v[0] = bflo(w.x); v[1] = bfhi(w.x); v[2] = bflo(w.y); v[3] = bfhi(w.y); v[4] = bflo(w.z); v[5] = bfhi(w.z); v[6] = bflo(w.w); v[7] = bfhi(w.w); }
; DI void finalize_tile(const Params& p, int l, int tile, LAS unsigned char* lds, int tid, int lane, int wave, const bool doq = true) {
;     ...
;         for (int h = 0; h < 4; ++h) {
;             const u32x4 ka = ka4[h], va = va4[h];
;             unpack8(ka, v);
;             float ss = 0.f;
; #pragma unroll
;             for (int e = 0; e < 8; ++e) { v[e] *= rckv; ss += v[e] * v[e]; }
;             ss = red16(ss, lane) + s3;
;             const float rk = rsqrtf(ss * (1.0f / 192.0f) + EPS);
;             const f32x4 g0 = kg0, g1 = kg1; const f32x2 gr1 = kgr1, gr2 = kgr2;
;             bf16_t* ko = KB + t * 768 + h * 192;
;             u32x4 o; o.x = pk2(v[0] * rk * g0.x, v[1] * rk * g0.y); o.y = pk2(v[2] * rk * g0.z, v[3] * rk * g0.w); o.z = pk2(v[4] * rk * g1.x, v[5] * rk * g1.y); o.w = pk2(v[6] * rk * g1.z, v[7] * rk * g1.w);
;             *(u32x4*)(ko + 8 * i) = o;
;             const float a1 = x1a * rk * gr1.x, b1 = x1b * rk * gr1.y, a2 = x2a * rk * gr2.x, b2 = x2b * rk * gr2.y;
;             *(unsigned*)(ko + 128 + 2 * i) = pk2(a1 * cs.x - a2 * sn.x, b1 * cs.y - b2 * sn.y);
;             *(unsigned*)(ko + 160 + 2 * i) = pk2(a1 * sn.x + a2 * cs.x, b1 * sn.y + b2 * cs.y);
;             unpack8(va, w);
;             u32x4 vo; vo.x = pk2(w[0] * rckv, w[1] * rckv); vo.y = pk2(w[2] * rckv, w[3] * rckv); vo.z = pk2(w[4] * rckv, w[5] * rckv); vo.w = pk2(w[6] * rckv, w[7] * rckv);
;             *(LAS u32x4*)(VL + tl * 512 + h * 128 + 8 * i) = vo;
;         }
;     }
;     __syncthreads();
;     {
;         const int b = t0 >> 12, s0 = t0 & 4095, h = tid >> 7, dv = tid & 127;
;         bf16_t* dst = VT + ((size_t)((b * 4 + h) * 128 + dv)) * SEQ + s0;
	v_lshlrev_b32_e32 v28, 16, v21
	v_and_b32_e32 v29, 0xffff0000, v21
	v_pk_mul_f32 v[24:25], v[0:1], v[58:59] op_sel_hi:[0,1]
	v_pk_mul_f32 v[22:23], v[0:1], v[56:57] op_sel_hi:[0,1]
	v_pk_mul_f32 v[24:25], v[60:61], v[24:25]
	v_pk_mul_f32 v[22:23], v[62:63], v[22:23]
	v_pk_mul_f32 v[26:27], v[54:55], v[24:25]
	v_pk_mul_f32 v[24:25], v[52:53], v[24:25]
	v_pk_fma_f32 v[26:27], v[52:53], v[22:23], v[26:27] neg_lo:[0,0,1] neg_hi:[0,0,1]
	v_pk_fma_f32 v[22:23], v[54:55], v[22:23], v[24:25]
	v_cvt_pk_bf16_f32 v0, v26, v27
	flat_store_dword v[44:45], v0 offset:1024
	v_cvt_pk_bf16_f32 v0, v22, v23
	v_lshlrev_b32_e32 v22, 16, v18
	v_and_b32_e32 v23, 0xffff0000, v18
	v_lshlrev_b32_e32 v24, 16, v19
	v_and_b32_e32 v25, 0xffff0000, v19
	v_lshlrev_b32_e32 v26, 16, v20
	v_and_b32_e32 v27, 0xffff0000, v20
	v_pk_mul_f32 v[18:19], v[42:43], v[22:23] op_sel_hi:[0,1]
	v_pk_mul_f32 v[20:21], v[42:43], v[24:25] op_sel_hi:[0,1]
	v_cvt_pk_bf16_f32 v18, v18, v19
	v_cvt_pk_bf16_f32 v19, v20, v21
	v_pk_mul_f32 v[20:21], v[42:43], v[26:27] op_sel_hi:[0,1]
	v_pk_mul_f32 v[22:23], v[42:43], v[28:29] op_sel_hi:[0,1]
	v_cvt_pk_bf16_f32 v20, v20, v21
	v_cvt_pk_bf16_f32 v21, v22, v23
	v_lshlrev_b32_e32 v22, 16, v14
	v_and_b32_e32 v23, 0xffff0000, v14
	flat_store_dword v[44:45], v0 offset:1088
	ds_write_b128 v88, v[18:21] offset:4608
	v_lshlrev_b32_e32 v18, 16, v15
	v_and_b32_e32 v19, 0xffff0000, v15
	v_pk_mul_f32 v[14:15], v[42:43], v[22:23] op_sel_hi:[0,1]
	v_pk_mul_f32 v[22:23], v[14:15], v[14:15]
	v_pk_mul_f32 v[18:19], v[42:43], v[18:19] op_sel_hi:[0,1]
	v_lshlrev_b32_e32 v20, 16, v16
	v_and_b32_e32 v21, 0xffff0000, v16
	v_pk_mul_f32 v[24:25], v[18:19], v[18:19]
	v_add_f32_e32 v0, v22, v23
	v_pk_mul_f32 v[20:21], v[42:43], v[20:21] op_sel_hi:[0,1]
	v_add_f32_e32 v0, v24, v0
	v_lshlrev_b32_e32 v16, 16, v17
	v_and_b32_e32 v17, 0xffff0000, v17
	v_pk_mul_f32 v[26:27], v[20:21], v[20:21]
	v_add_f32_e32 v0, v25, v0
	v_pk_mul_f32 v[16:17], v[42:43], v[16:17] op_sel_hi:[0,1]
	v_add_f32_e32 v0, v26, v0
	v_pk_mul_f32 v[28:29], v[16:17], v[16:17]
	v_add_f32_e32 v0, v27, v0
	v_add_f32_e32 v0, v28, v0
	v_add_f32_e32 v0, v29, v0
	s_nop 1
	v_add_f32_dpp v0, v0, v0 row_ror:1 row_mask:0xf bank_mask:0xf bound_ctrl:1
	s_nop 1
	v_add_f32_dpp v0, v0, v0 row_ror:2 row_mask:0xf bank_mask:0xf bound_ctrl:1
	s_nop 1
	v_add_f32_dpp v0, v0, v0 row_ror:4 row_mask:0xf bank_mask:0xf bound_ctrl:1
	s_nop 1
	v_add_f32_dpp v0, v0, v0 row_ror:8 row_mask:0xf bank_mask:0xf bound_ctrl:1
	v_add_f32_e32 v0, v68, v0
	v_fmamk_f32 v0, v0, 0x3baaaaab, v228
	v_cmp_gt_f32_e32 vcc, s95, v0
	v_mul_f32_e32 v22, 0x4b800000, v0
	s_nop 0
	v_cndmask_b32_e32 v0, v0, v22, vcc
	v_rsq_f32_e32 v0, v0
	s_nop 0
	v_mul_f32_e32 v22, 0x45800000, v0
	v_cndmask_b32_e32 v0, v0, v22, vcc
	v_pk_mul_f32 v[14:15], v[14:15], v[0:1] op_sel_hi:[1,0]
	s_nop 0
	v_pk_mul_f32 v[10:11], v[10:11], v[14:15]
	v_pk_mul_f32 v[14:15], v[18:19], v[0:1] op_sel_hi:[1,0]
	v_cvt_pk_bf16_f32 v10, v10, v11
	v_pk_mul_f32 v[12:13], v[12:13], v[14:15]
	s_nop 0
	v_cvt_pk_bf16_f32 v11, v12, v13
	v_pk_mul_f32 v[12:13], v[20:21], v[0:1] op_sel_hi:[1,0]
	s_nop 0
	v_pk_mul_f32 v[6:7], v[6:7], v[12:13]
	s_nop 0
	v_cvt_pk_bf16_f32 v12, v6, v7
	v_pk_mul_f32 v[6:7], v[16:17], v[0:1] op_sel_hi:[1,0]
	s_nop 0
	v_pk_mul_f32 v[6:7], v[8:9], v[6:7]
	v_pk_mul_f32 v[8:9], v[0:1], v[58:59] op_sel_hi:[0,1]
	v_cvt_pk_bf16_f32 v13, v6, v7
	v_pk_mul_f32 v[6:7], v[0:1], v[56:57] op_sel_hi:[0,1]
	v_pk_mul_f32 v[8:9], v[60:61], v[8:9]
	flat_store_dwordx4 v[38:39], v[10:13] offset:1152
	v_pk_mul_f32 v[6:7], v[62:63], v[6:7]
	s_nop 0
	v_pk_mul_f32 v[10:11], v[54:55], v[8:9]
	v_pk_mul_f32 v[8:9], v[52:53], v[8:9]
	v_pk_fma_f32 v[10:11], v[52:53], v[6:7], v[10:11] neg_lo:[0,0,1] neg_hi:[0,0,1]
	v_pk_fma_f32 v[6:7], v[54:55], v[6:7], v[8:9]
	v_cvt_pk_bf16_f32 v0, v10, v11
	flat_store_dword v[44:45], v0 offset:1408
	v_cvt_pk_bf16_f32 v0, v6, v7
	v_lshlrev_b32_e32 v6, 16, v2
	v_and_b32_e32 v7, 0xffff0000, v2
	v_lshlrev_b32_e32 v8, 16, v3
	v_and_b32_e32 v9, 0xffff0000, v3
	v_lshlrev_b32_e32 v10, 16, v4
	v_and_b32_e32 v11, 0xffff0000, v4
	v_lshlrev_b32_e32 v12, 16, v5
	v_and_b32_e32 v13, 0xffff0000, v5
	v_pk_mul_f32 v[2:3], v[42:43], v[6:7] op_sel_hi:[0,1]
	v_pk_mul_f32 v[4:5], v[42:43], v[8:9] op_sel_hi:[0,1]
	v_cvt_pk_bf16_f32 v2, v2, v3
	v_cvt_pk_bf16_f32 v3, v4, v5
	v_pk_mul_f32 v[4:5], v[42:43], v[10:11] op_sel_hi:[0,1]
	v_pk_mul_f32 v[6:7], v[42:43], v[12:13] op_sel_hi:[0,1]
	v_cvt_pk_bf16_f32 v4, v4, v5
	v_cvt_pk_bf16_f32 v5, v6, v7
	flat_store_dword v[44:45], v0 offset:1472
	ds_write_b128 v88, v[2:5] offset:4864
	v_add_u32_e32 v2, s1, v92
	v_ashrrev_i32_e32 v3, 31, v2
	v_lshlrev_b64 v[2:3], 13, v[2:3]
	v_lshl_add_u64 v[2:3], s[6:7], 0, v[2:3]
	v_lshl_add_u32 v0, v92, 1, 0
	s_waitcnt lgkmcnt(0)
	s_barrier
; DI void finalize_tile(const Params& p, int l, int tile, LAS unsigned char* lds, int tid, int lane, int wave, const bool doq = true) {
;     ...
;     {
;         const int b = t0 >> 12, s0 = t0 & 4095, h = tid >> 7, dv = tid & 127;
;         bf16_t* dst = VT + ((size_t)((b * 4 + h) * 128 + dv)) * SEQ + s0;
; #pragma unroll
;         for (int q = 0; q < 8; ++q) { unsigned wv[4];
; #pragma unroll
;             for (int e = 0; e < 4; ++e) wv[e] = (unsigned)VL[(q * 8 + 2 * e) * 512 + tid] | ((unsigned)VL[(q * 8 + 2 * e + 1) * 512 + tid] << 16);
;             *(u32x4*)(dst + q * 8) = (u32x4){wv[0], wv[1], wv[2], wv[3]}; }
;     }
;     __syncthreads();
	v_lshl_add_u64 v[6:7], v[2:3], 0, s[92:93]
	s_mov_b64 s[0:1], 0xe600000
	v_lshl_add_u64 v[8:9], v[6:7], 0, s[0:1]
	s_mov_b32 s0, 0xe600000
	v_add_co_u32_e32 v6, vcc, s0, v6
	v_addc_co_u32_e32 v7, vcc, 0, v7, vcc
	ds_read_u16 v2, v0
	ds_read_u16 v10, v0 offset:1024
	ds_read_u16 v3, v0 offset:2048
	ds_read_u16 v11, v0 offset:3072
	ds_read_u16 v4, v0 offset:4096
	ds_read_u16 v12, v0 offset:5120
	ds_read_u16 v5, v0 offset:6144
	ds_read_u16 v13, v0 offset:7168
	s_waitcnt lgkmcnt(0)
	v_lshl_or_b32 v2, v10, 16, v2
	v_lshl_or_b32 v3, v11, 16, v3
	v_lshl_or_b32 v4, v12, 16, v4
	v_lshl_or_b32 v5, v13, 16, v5
	flat_store_dwordx4 v[6:7], v[2:5]
	ds_read_u16 v2, v0 offset:8192
	ds_read_u16 v10, v0 offset:9216
	ds_read_u16 v3, v0 offset:10240
	ds_read_u16 v11, v0 offset:11264
	ds_read_u16 v4, v0 offset:12288
	ds_read_u16 v12, v0 offset:13312
	ds_read_u16 v5, v0 offset:14336
	ds_read_u16 v13, v0 offset:15360
	s_waitcnt lgkmcnt(0)
	v_lshl_or_b32 v2, v10, 16, v2
	v_lshl_or_b32 v3, v11, 16, v3
	v_lshl_or_b32 v4, v12, 16, v4
	v_lshl_or_b32 v5, v13, 16, v5
	flat_store_dwordx4 v[8:9], v[2:5] offset:16
	ds_read_u16 v2, v0 offset:16384
	ds_read_u16 v10, v0 offset:17408
	ds_read_u16 v3, v0 offset:18432
	ds_read_u16 v11, v0 offset:19456
	ds_read_u16 v4, v0 offset:20480
	ds_read_u16 v12, v0 offset:21504
	ds_read_u16 v5, v0 offset:22528
	ds_read_u16 v13, v0 offset:23552
	s_waitcnt lgkmcnt(0)
	v_lshl_or_b32 v2, v10, 16, v2
	v_lshl_or_b32 v3, v11, 16, v3
	v_lshl_or_b32 v4, v12, 16, v4
	v_lshl_or_b32 v5, v13, 16, v5
	flat_store_dwordx4 v[8:9], v[2:5] offset:32
	ds_read_u16 v2, v0 offset:24576
	ds_read_u16 v10, v0 offset:25600
	ds_read_u16 v3, v0 offset:26624
	ds_read_u16 v11, v0 offset:27648
	ds_read_u16 v4, v0 offset:28672
	ds_read_u16 v12, v0 offset:29696
	ds_read_u16 v5, v0 offset:30720
	ds_read_u16 v13, v0 offset:31744
	s_waitcnt lgkmcnt(0)
	v_lshl_or_b32 v2, v10, 16, v2
	v_lshl_or_b32 v3, v11, 16, v3
	v_lshl_or_b32 v4, v12, 16, v4
	v_lshl_or_b32 v5, v13, 16, v5
	flat_store_dwordx4 v[8:9], v[2:5] offset:48
	ds_read_u16 v2, v0 offset:32768
	ds_read_u16 v10, v0 offset:33792
	ds_read_u16 v3, v0 offset:34816
	ds_read_u16 v11, v0 offset:35840
	ds_read_u16 v4, v0 offset:36864
	ds_read_u16 v12, v0 offset:37888
	ds_read_u16 v5, v0 offset:38912
	ds_read_u16 v13, v0 offset:39936
	s_waitcnt lgkmcnt(0)
	v_lshl_or_b32 v2, v10, 16, v2
	v_lshl_or_b32 v3, v11, 16, v3
	v_lshl_or_b32 v4, v12, 16, v4
	v_lshl_or_b32 v5, v13, 16, v5
	flat_store_dwordx4 v[8:9], v[2:5] offset:64
	ds_read_u16 v2, v0 offset:40960
	ds_read_u16 v10, v0 offset:41984
	ds_read_u16 v3, v0 offset:43008
	ds_read_u16 v11, v0 offset:44032
	ds_read_u16 v4, v0 offset:45056
	ds_read_u16 v12, v0 offset:46080
	ds_read_u16 v5, v0 offset:47104
	ds_read_u16 v13, v0 offset:48128
	s_waitcnt lgkmcnt(0)
	v_lshl_or_b32 v2, v10, 16, v2
	v_lshl_or_b32 v3, v11, 16, v3
	v_lshl_or_b32 v4, v12, 16, v4
	v_lshl_or_b32 v5, v13, 16, v5
	flat_store_dwordx4 v[8:9], v[2:5] offset:80
	ds_read_u16 v2, v0 offset:49152
	ds_read_u16 v10, v0 offset:50176
	ds_read_u16 v3, v0 offset:51200
	ds_read_u16 v11, v0 offset:52224
	ds_read_u16 v4, v0 offset:53248
	ds_read_u16 v12, v0 offset:54272
	ds_read_u16 v5, v0 offset:55296
	ds_read_u16 v13, v0 offset:56320
	s_waitcnt lgkmcnt(0)
	v_lshl_or_b32 v2, v10, 16, v2
	v_lshl_or_b32 v3, v11, 16, v3
	v_lshl_or_b32 v4, v12, 16, v4
	v_lshl_or_b32 v5, v13, 16, v5
	flat_store_dwordx4 v[8:9], v[2:5] offset:96
	ds_read_u16 v2, v0 offset:57344
	ds_read_u16 v10, v0 offset:58368
	ds_read_u16 v3, v0 offset:59392
	ds_read_u16 v11, v0 offset:60416
	ds_read_u16 v4, v0 offset:61440
	ds_read_u16 v12, v0 offset:62464
	ds_read_u16 v5, v0 offset:63488
	ds_read_u16 v13, v0 offset:64512
	s_waitcnt lgkmcnt(0)
	v_lshl_or_b32 v2, v10, 16, v2
	v_lshl_or_b32 v3, v11, 16, v3
	v_lshl_or_b32 v4, v12, 16, v4
	v_lshl_or_b32 v5, v13, 16, v5
	flat_store_dwordx4 v[8:9], v[2:5] offset:112
	s_waitcnt lgkmcnt(0)
	s_barrier
	s_cbranch_scc0 .LBB0_366
